# v49 with nt hints on the FFN-in tail transposer's loads and stores
# speedup vs baseline: 1.0058x; 1.0019x over previous
.LBB0_1906:
	s_waitcnt vmcnt(0)
	s_mov_b32 s2, s86
	s_barrier
	s_cmpk_eq_u32 s84, 0x100
	s_cbranch_scc0 .Lwf_done
	v_readlane_b32 s94, v254, 0
	v_readfirstlane_b32 s95, v0
	s_nop 3
	s_cmpk_lt_u32 s94, 0x80
	s_cbranch_scc1 .Lwf_done
	s_lshr_b32 s95, s95, 6
	s_sub_u32 s94, s94, 0x80
	s_lshl_b32 s94, s94, 3
	s_add_u32 s94, s94, s95
	v_readlane_b32 s96, v254, 2
	v_readlane_b32 s97, v254, 3
	s_nop 3
	s_sub_u32 s96, s96, 0x28
	s_subb_u32 s97, s97, 0
	s_load_dwordx2 s[100:101], s[96:97], 0x0
	s_add_u32 s94, s94, 0x600
	v_and_b32_e32 v2, 63, v0
	v_lshrrev_b32_e32 v3, 3, v2
	v_and_b32_e32 v4, 7, v2
	v_lshlrev_b32_e32 v5, 14, v3
	v_lshl_add_u32 v5, v4, 4, v5
	v_add_u32_e32 v6, 0x0, v5
	v_add_u32_e32 v7, 0x20000, v5
	v_add_u32_e32 v8, 0x40000, v5
	v_add_u32_e32 v9, 0x60000, v5
	v_add_u32_e32 v10, 0x80000, v5
	v_add_u32_e32 v11, 0xa0000, v5
	v_add_u32_e32 v12, 0xc0000, v5
	v_add_u32_e32 v13, 0xe0000, v5
	s_lshl_b32 s95, s95, 14
	v_mul_u32_u24_e32 v14, 0x84, v3
	v_lshl_add_u32 v14, v4, 4, v14
	v_add_u32_e32 v14, s95, v14
	v_mul_u32_u24_e32 v15, 0x420, v4
	v_lshl_add_u32 v15, v3, 2, v15
	v_add_u32_e32 v15, s95, v15
	v_mul_u32_u24_e32 v16, 0x5600, v3
	v_lshl_add_u32 v16, v4, 4, v16
	v_add_u32_e32 v17, 0x2b000, v16
	v_add_u32_e32 v18, 0x56000, v16
	v_add_u32_e32 v19, 0x81000, v16
	s_waitcnt lgkmcnt(0)
	s_mov_b32 s95, s94
	s_lshr_b32 vcc_lo, s95, 7
	s_and_b32 vcc_hi, s95, 0x7f
	s_lshl_b32 vcc_lo, vcc_lo, 20
	s_lshl_b32 vcc_hi, vcc_hi, 7
	s_add_u32 s96, s100, vcc_lo
	s_addc_u32 s97, s101, 0
	s_add_u32 s96, s96, vcc_hi
	s_addc_u32 s97, s97, 0
	global_load_dwordx4 v[20:23], v6, s[96:97] nt
	global_load_dwordx4 v[24:27], v7, s[96:97] nt
	global_load_dwordx4 v[28:31], v8, s[96:97] nt
	global_load_dwordx4 v[32:35], v9, s[96:97] nt
	global_load_dwordx4 v[36:39], v10, s[96:97] nt
	global_load_dwordx4 v[40:43], v11, s[96:97] nt
	global_load_dwordx4 v[44:47], v12, s[96:97] nt
	global_load_dwordx4 v[48:51], v13, s[96:97] nt
	s_add_u32 s95, s94, 0x400
	s_lshr_b32 vcc_lo, s95, 7
	s_and_b32 vcc_hi, s95, 0x7f
	s_lshl_b32 vcc_lo, vcc_lo, 20
	s_lshl_b32 vcc_hi, vcc_hi, 7
	s_add_u32 s96, s100, vcc_lo
	s_addc_u32 s97, s101, 0
	s_add_u32 s96, s96, vcc_hi
	s_addc_u32 s97, s97, 0
	global_load_dwordx4 v[100:103], v6, s[96:97] nt
	global_load_dwordx4 v[104:107], v7, s[96:97] nt
	global_load_dwordx4 v[108:111], v8, s[96:97] nt
	global_load_dwordx4 v[112:115], v9, s[96:97] nt
	global_load_dwordx4 v[116:119], v10, s[96:97] nt
	global_load_dwordx4 v[120:123], v11, s[96:97] nt
	global_load_dwordx4 v[124:127], v12, s[96:97] nt
	global_load_dwordx4 v[128:131], v13, s[96:97] nt
	s_waitcnt vmcnt(15)
	ds_write_b32 v14, v20 offset:0
	ds_write_b32 v14, v21 offset:4
	ds_write_b32 v14, v22 offset:8
	ds_write_b32 v14, v23 offset:12
	s_waitcnt vmcnt(14)
	ds_write_b32 v14, v24 offset:1056
	ds_write_b32 v14, v25 offset:1060
	ds_write_b32 v14, v26 offset:1064
	ds_write_b32 v14, v27 offset:1068
	s_waitcnt vmcnt(13)
	ds_write_b32 v14, v28 offset:2112
	ds_write_b32 v14, v29 offset:2116
	ds_write_b32 v14, v30 offset:2120
	ds_write_b32 v14, v31 offset:2124
	s_waitcnt vmcnt(12)
	ds_write_b32 v14, v32 offset:3168
	ds_write_b32 v14, v33 offset:3172
	ds_write_b32 v14, v34 offset:3176
	ds_write_b32 v14, v35 offset:3180
	s_waitcnt vmcnt(11)
	ds_write_b32 v14, v36 offset:4224
	ds_write_b32 v14, v37 offset:4228
	ds_write_b32 v14, v38 offset:4232
	ds_write_b32 v14, v39 offset:4236
	s_waitcnt vmcnt(10)
	ds_write_b32 v14, v40 offset:5280
	ds_write_b32 v14, v41 offset:5284
	ds_write_b32 v14, v42 offset:5288
	ds_write_b32 v14, v43 offset:5292
	s_waitcnt vmcnt(9)
	ds_write_b32 v14, v44 offset:6336
	ds_write_b32 v14, v45 offset:6340
	ds_write_b32 v14, v46 offset:6344
	ds_write_b32 v14, v47 offset:6348
	s_waitcnt vmcnt(8)
	ds_write_b32 v14, v48 offset:7392
	ds_write_b32 v14, v49 offset:7396
	ds_write_b32 v14, v50 offset:7400
	ds_write_b32 v14, v51 offset:7404
	s_add_u32 s95, s94, 0x800
	s_lshr_b32 vcc_lo, s95, 7
	s_and_b32 vcc_hi, s95, 0x7f
	s_lshl_b32 vcc_lo, vcc_lo, 20
	s_lshl_b32 vcc_hi, vcc_hi, 7
	s_add_u32 s96, s100, vcc_lo
	s_addc_u32 s97, s101, 0
	s_add_u32 s96, s96, vcc_hi
	s_addc_u32 s97, s97, 0
	global_load_dwordx4 v[20:23], v6, s[96:97] nt
	global_load_dwordx4 v[24:27], v7, s[96:97] nt
	global_load_dwordx4 v[28:31], v8, s[96:97] nt
	global_load_dwordx4 v[32:35], v9, s[96:97] nt
	global_load_dwordx4 v[36:39], v10, s[96:97] nt
	global_load_dwordx4 v[40:43], v11, s[96:97] nt
	global_load_dwordx4 v[44:47], v12, s[96:97] nt
	global_load_dwordx4 v[48:51], v13, s[96:97] nt
	ds_read2_b32 v[52:53], v15 offset0:0 offset1:33
	ds_read2_b32 v[54:55], v15 offset0:66 offset1:99
	ds_read2_b32 v[56:57], v15 offset0:132 offset1:165
	ds_read2_b32 v[58:59], v15 offset0:198 offset1:231
	ds_read2_b32 v[60:61], v15 offset0:8 offset1:41
	ds_read2_b32 v[62:63], v15 offset0:74 offset1:107
	ds_read2_b32 v[64:65], v15 offset0:140 offset1:173
	ds_read2_b32 v[66:67], v15 offset0:206 offset1:239
	ds_read2_b32 v[68:69], v15 offset0:16 offset1:49
	ds_read2_b32 v[70:71], v15 offset0:82 offset1:115
	ds_read2_b32 v[72:73], v15 offset0:148 offset1:181
	ds_read2_b32 v[74:75], v15 offset0:214 offset1:247
	ds_read2_b32 v[76:77], v15 offset0:24 offset1:57
	ds_read2_b32 v[78:79], v15 offset0:90 offset1:123
	ds_read2_b32 v[80:81], v15 offset0:156 offset1:189
	ds_read2_b32 v[82:83], v15 offset0:222 offset1:255
	s_mov_b32 s95, s94
	s_lshr_b32 vcc_lo, s95, 7
	s_and_b32 vcc_hi, s95, 0x7f
	s_mul_i32 vcc_hi, vcc_hi, 0xac000
	s_lshl_b32 vcc_lo, vcc_lo, 7
	s_add_u32 s98, s66, 0x12d00000
	s_addc_u32 s99, s67, 0
	s_add_u32 s98, s98, vcc_hi
	s_addc_u32 s99, s99, 0
	s_add_u32 s98, s98, vcc_lo
	s_addc_u32 s99, s99, 0
	s_waitcnt lgkmcnt(0)
	v_cvt_pk_bf16_f32 v84, v52, v53
	v_cvt_pk_bf16_f32 v85, v54, v55
	v_cvt_pk_bf16_f32 v86, v56, v57
	v_cvt_pk_bf16_f32 v87, v58, v59
	v_cvt_pk_bf16_f32 v88, v60, v61
	v_cvt_pk_bf16_f32 v89, v62, v63
	v_cvt_pk_bf16_f32 v90, v64, v65
	v_cvt_pk_bf16_f32 v91, v66, v67
	v_cvt_pk_bf16_f32 v92, v68, v69
	v_cvt_pk_bf16_f32 v93, v70, v71
	v_cvt_pk_bf16_f32 v94, v72, v73
	v_cvt_pk_bf16_f32 v95, v74, v75
	v_cvt_pk_bf16_f32 v96, v76, v77
	v_cvt_pk_bf16_f32 v97, v78, v79
	v_cvt_pk_bf16_f32 v98, v80, v81
	v_cvt_pk_bf16_f32 v99, v82, v83
	global_store_dwordx4 v16, v[84:87], s[98:99] nt
	global_store_dwordx4 v17, v[88:91], s[98:99] nt
	global_store_dwordx4 v18, v[92:95], s[98:99] nt
	global_store_dwordx4 v19, v[96:99], s[98:99] nt
	s_waitcnt vmcnt(19)
	ds_write_b32 v14, v100 offset:0
	ds_write_b32 v14, v101 offset:4
	ds_write_b32 v14, v102 offset:8
	ds_write_b32 v14, v103 offset:12
	s_waitcnt vmcnt(18)
	ds_write_b32 v14, v104 offset:1056
	ds_write_b32 v14, v105 offset:1060
	ds_write_b32 v14, v106 offset:1064
	ds_write_b32 v14, v107 offset:1068
	s_waitcnt vmcnt(17)
	ds_write_b32 v14, v108 offset:2112
	ds_write_b32 v14, v109 offset:2116
	ds_write_b32 v14, v110 offset:2120
	ds_write_b32 v14, v111 offset:2124
	s_waitcnt vmcnt(16)
	ds_write_b32 v14, v112 offset:3168
	ds_write_b32 v14, v113 offset:3172
	ds_write_b32 v14, v114 offset:3176
	ds_write_b32 v14, v115 offset:3180
	s_waitcnt vmcnt(15)
	ds_write_b32 v14, v116 offset:4224
	ds_write_b32 v14, v117 offset:4228
	ds_write_b32 v14, v118 offset:4232
	ds_write_b32 v14, v119 offset:4236
	s_waitcnt vmcnt(14)
	ds_write_b32 v14, v120 offset:5280
	ds_write_b32 v14, v121 offset:5284
	ds_write_b32 v14, v122 offset:5288
	ds_write_b32 v14, v123 offset:5292
	s_waitcnt vmcnt(13)
	ds_write_b32 v14, v124 offset:6336
	ds_write_b32 v14, v125 offset:6340
	ds_write_b32 v14, v126 offset:6344
	ds_write_b32 v14, v127 offset:6348
	s_waitcnt vmcnt(12)
	ds_write_b32 v14, v128 offset:7392
	ds_write_b32 v14, v129 offset:7396
	ds_write_b32 v14, v130 offset:7400
	ds_write_b32 v14, v131 offset:7404
	s_add_u32 s95, s94, 0xc00
	s_lshr_b32 vcc_lo, s95, 7
	s_and_b32 vcc_hi, s95, 0x7f
	s_lshl_b32 vcc_lo, vcc_lo, 20
	s_lshl_b32 vcc_hi, vcc_hi, 7
	s_add_u32 s96, s100, vcc_lo
	s_addc_u32 s97, s101, 0
	s_add_u32 s96, s96, vcc_hi
	s_addc_u32 s97, s97, 0
	global_load_dwordx4 v[100:103], v6, s[96:97] nt
	global_load_dwordx4 v[104:107], v7, s[96:97] nt
	global_load_dwordx4 v[108:111], v8, s[96:97] nt
	global_load_dwordx4 v[112:115], v9, s[96:97] nt
	global_load_dwordx4 v[116:119], v10, s[96:97] nt
	global_load_dwordx4 v[120:123], v11, s[96:97] nt
	global_load_dwordx4 v[124:127], v12, s[96:97] nt
	global_load_dwordx4 v[128:131], v13, s[96:97] nt
	ds_read2_b32 v[52:53], v15 offset0:0 offset1:33
	ds_read2_b32 v[54:55], v15 offset0:66 offset1:99
	ds_read2_b32 v[56:57], v15 offset0:132 offset1:165
	ds_read2_b32 v[58:59], v15 offset0:198 offset1:231
	ds_read2_b32 v[60:61], v15 offset0:8 offset1:41
	ds_read2_b32 v[62:63], v15 offset0:74 offset1:107
	ds_read2_b32 v[64:65], v15 offset0:140 offset1:173
	ds_read2_b32 v[66:67], v15 offset0:206 offset1:239
	ds_read2_b32 v[68:69], v15 offset0:16 offset1:49
	ds_read2_b32 v[70:71], v15 offset0:82 offset1:115
	ds_read2_b32 v[72:73], v15 offset0:148 offset1:181
	ds_read2_b32 v[74:75], v15 offset0:214 offset1:247
	ds_read2_b32 v[76:77], v15 offset0:24 offset1:57
	ds_read2_b32 v[78:79], v15 offset0:90 offset1:123
	ds_read2_b32 v[80:81], v15 offset0:156 offset1:189
	ds_read2_b32 v[82:83], v15 offset0:222 offset1:255
	s_add_u32 s95, s94, 0x400
	s_lshr_b32 vcc_lo, s95, 7
	s_and_b32 vcc_hi, s95, 0x7f
	s_mul_i32 vcc_hi, vcc_hi, 0xac000
	s_lshl_b32 vcc_lo, vcc_lo, 7
	s_add_u32 s98, s66, 0x12d00000
	s_addc_u32 s99, s67, 0
	s_add_u32 s98, s98, vcc_hi
	s_addc_u32 s99, s99, 0
	s_add_u32 s98, s98, vcc_lo
	s_addc_u32 s99, s99, 0
	s_waitcnt lgkmcnt(0)
	v_cvt_pk_bf16_f32 v84, v52, v53
	v_cvt_pk_bf16_f32 v85, v54, v55
	v_cvt_pk_bf16_f32 v86, v56, v57
	v_cvt_pk_bf16_f32 v87, v58, v59
	v_cvt_pk_bf16_f32 v88, v60, v61
	v_cvt_pk_bf16_f32 v89, v62, v63
	v_cvt_pk_bf16_f32 v90, v64, v65
	v_cvt_pk_bf16_f32 v91, v66, v67
	v_cvt_pk_bf16_f32 v92, v68, v69
	v_cvt_pk_bf16_f32 v93, v70, v71
	v_cvt_pk_bf16_f32 v94, v72, v73
	v_cvt_pk_bf16_f32 v95, v74, v75
	v_cvt_pk_bf16_f32 v96, v76, v77
	v_cvt_pk_bf16_f32 v97, v78, v79
	v_cvt_pk_bf16_f32 v98, v80, v81
	v_cvt_pk_bf16_f32 v99, v82, v83
	global_store_dwordx4 v16, v[84:87], s[98:99] nt
	global_store_dwordx4 v17, v[88:91], s[98:99] nt
	global_store_dwordx4 v18, v[92:95], s[98:99] nt
	global_store_dwordx4 v19, v[96:99], s[98:99] nt
	s_waitcnt vmcnt(23)
	ds_write_b32 v14, v20 offset:0
	ds_write_b32 v14, v21 offset:4
	ds_write_b32 v14, v22 offset:8
	ds_write_b32 v14, v23 offset:12
	s_waitcnt vmcnt(22)
	ds_write_b32 v14, v24 offset:1056
	ds_write_b32 v14, v25 offset:1060
	ds_write_b32 v14, v26 offset:1064
	ds_write_b32 v14, v27 offset:1068
	s_waitcnt vmcnt(21)
	ds_write_b32 v14, v28 offset:2112
	ds_write_b32 v14, v29 offset:2116
	ds_write_b32 v14, v30 offset:2120
	ds_write_b32 v14, v31 offset:2124
	s_waitcnt vmcnt(20)
	ds_write_b32 v14, v32 offset:3168
	ds_write_b32 v14, v33 offset:3172
	ds_write_b32 v14, v34 offset:3176
	ds_write_b32 v14, v35 offset:3180
	s_waitcnt vmcnt(19)
	ds_write_b32 v14, v36 offset:4224
	ds_write_b32 v14, v37 offset:4228
	ds_write_b32 v14, v38 offset:4232
	ds_write_b32 v14, v39 offset:4236
	s_waitcnt vmcnt(18)
	ds_write_b32 v14, v40 offset:5280
	ds_write_b32 v14, v41 offset:5284
	ds_write_b32 v14, v42 offset:5288
	ds_write_b32 v14, v43 offset:5292
	s_waitcnt vmcnt(17)
	ds_write_b32 v14, v44 offset:6336
	ds_write_b32 v14, v45 offset:6340
	ds_write_b32 v14, v46 offset:6344
	ds_write_b32 v14, v47 offset:6348
	s_waitcnt vmcnt(16)
	ds_write_b32 v14, v48 offset:7392
	ds_write_b32 v14, v49 offset:7396
	ds_write_b32 v14, v50 offset:7400
	ds_write_b32 v14, v51 offset:7404
	s_add_u32 s95, s94, 0x1000
	s_lshr_b32 vcc_lo, s95, 7
	s_and_b32 vcc_hi, s95, 0x7f
	s_lshl_b32 vcc_lo, vcc_lo, 20
	s_lshl_b32 vcc_hi, vcc_hi, 7
	s_add_u32 s96, s100, vcc_lo
	s_addc_u32 s97, s101, 0
	s_add_u32 s96, s96, vcc_hi
	s_addc_u32 s97, s97, 0
	global_load_dwordx4 v[20:23], v6, s[96:97] nt
	global_load_dwordx4 v[24:27], v7, s[96:97] nt
	global_load_dwordx4 v[28:31], v8, s[96:97] nt
	global_load_dwordx4 v[32:35], v9, s[96:97] nt
	global_load_dwordx4 v[36:39], v10, s[96:97] nt
	global_load_dwordx4 v[40:43], v11, s[96:97] nt
	global_load_dwordx4 v[44:47], v12, s[96:97] nt
	global_load_dwordx4 v[48:51], v13, s[96:97] nt
	ds_read2_b32 v[52:53], v15 offset0:0 offset1:33
	ds_read2_b32 v[54:55], v15 offset0:66 offset1:99
	ds_read2_b32 v[56:57], v15 offset0:132 offset1:165
	ds_read2_b32 v[58:59], v15 offset0:198 offset1:231
	ds_read2_b32 v[60:61], v15 offset0:8 offset1:41
	ds_read2_b32 v[62:63], v15 offset0:74 offset1:107
	ds_read2_b32 v[64:65], v15 offset0:140 offset1:173
	ds_read2_b32 v[66:67], v15 offset0:206 offset1:239
	ds_read2_b32 v[68:69], v15 offset0:16 offset1:49
	ds_read2_b32 v[70:71], v15 offset0:82 offset1:115
	ds_read2_b32 v[72:73], v15 offset0:148 offset1:181
	ds_read2_b32 v[74:75], v15 offset0:214 offset1:247
	ds_read2_b32 v[76:77], v15 offset0:24 offset1:57
	ds_read2_b32 v[78:79], v15 offset0:90 offset1:123
	ds_read2_b32 v[80:81], v15 offset0:156 offset1:189
	ds_read2_b32 v[82:83], v15 offset0:222 offset1:255
	s_add_u32 s95, s94, 0x800
	s_lshr_b32 vcc_lo, s95, 7
	s_and_b32 vcc_hi, s95, 0x7f
	s_mul_i32 vcc_hi, vcc_hi, 0xac000
	s_lshl_b32 vcc_lo, vcc_lo, 7
	s_add_u32 s98, s66, 0x12d00000
	s_addc_u32 s99, s67, 0
	s_add_u32 s98, s98, vcc_hi
	s_addc_u32 s99, s99, 0
	s_add_u32 s98, s98, vcc_lo
	s_addc_u32 s99, s99, 0
	s_waitcnt lgkmcnt(0)
	v_cvt_pk_bf16_f32 v84, v52, v53
	v_cvt_pk_bf16_f32 v85, v54, v55
	v_cvt_pk_bf16_f32 v86, v56, v57
	v_cvt_pk_bf16_f32 v87, v58, v59
	v_cvt_pk_bf16_f32 v88, v60, v61
	v_cvt_pk_bf16_f32 v89, v62, v63
	v_cvt_pk_bf16_f32 v90, v64, v65
	v_cvt_pk_bf16_f32 v91, v66, v67
	v_cvt_pk_bf16_f32 v92, v68, v69
	v_cvt_pk_bf16_f32 v93, v70, v71
	v_cvt_pk_bf16_f32 v94, v72, v73
	v_cvt_pk_bf16_f32 v95, v74, v75
	v_cvt_pk_bf16_f32 v96, v76, v77
	v_cvt_pk_bf16_f32 v97, v78, v79
	v_cvt_pk_bf16_f32 v98, v80, v81
	v_cvt_pk_bf16_f32 v99, v82, v83
	global_store_dwordx4 v16, v[84:87], s[98:99] nt
	global_store_dwordx4 v17, v[88:91], s[98:99] nt
	global_store_dwordx4 v18, v[92:95], s[98:99] nt
	global_store_dwordx4 v19, v[96:99], s[98:99] nt
	s_waitcnt vmcnt(23)
	ds_write_b32 v14, v100 offset:0
	ds_write_b32 v14, v101 offset:4
	ds_write_b32 v14, v102 offset:8
	ds_write_b32 v14, v103 offset:12
	s_waitcnt vmcnt(22)
	ds_write_b32 v14, v104 offset:1056
	ds_write_b32 v14, v105 offset:1060
	ds_write_b32 v14, v106 offset:1064
	ds_write_b32 v14, v107 offset:1068
	s_waitcnt vmcnt(21)
	ds_write_b32 v14, v108 offset:2112
	ds_write_b32 v14, v109 offset:2116
	ds_write_b32 v14, v110 offset:2120
	ds_write_b32 v14, v111 offset:2124
	s_waitcnt vmcnt(20)
	ds_write_b32 v14, v112 offset:3168
	ds_write_b32 v14, v113 offset:3172
	ds_write_b32 v14, v114 offset:3176
	ds_write_b32 v14, v115 offset:3180
	s_waitcnt vmcnt(19)
	ds_write_b32 v14, v116 offset:4224
	ds_write_b32 v14, v117 offset:4228
	ds_write_b32 v14, v118 offset:4232
	ds_write_b32 v14, v119 offset:4236
	s_waitcnt vmcnt(18)
	ds_write_b32 v14, v120 offset:5280
	ds_write_b32 v14, v121 offset:5284
	ds_write_b32 v14, v122 offset:5288
	ds_write_b32 v14, v123 offset:5292
	s_waitcnt vmcnt(17)
	ds_write_b32 v14, v124 offset:6336
	ds_write_b32 v14, v125 offset:6340
	ds_write_b32 v14, v126 offset:6344
	ds_write_b32 v14, v127 offset:6348
	s_waitcnt vmcnt(16)
	ds_write_b32 v14, v128 offset:7392
	ds_write_b32 v14, v129 offset:7396
	ds_write_b32 v14, v130 offset:7400
	ds_write_b32 v14, v131 offset:7404
	s_add_u32 s95, s94, 0x1400
	s_lshr_b32 vcc_lo, s95, 7
	s_and_b32 vcc_hi, s95, 0x7f
	s_lshl_b32 vcc_lo, vcc_lo, 20
	s_lshl_b32 vcc_hi, vcc_hi, 7
	s_add_u32 s96, s100, vcc_lo
	s_addc_u32 s97, s101, 0
	s_add_u32 s96, s96, vcc_hi
	s_addc_u32 s97, s97, 0
	global_load_dwordx4 v[100:103], v6, s[96:97] nt
	global_load_dwordx4 v[104:107], v7, s[96:97] nt
	global_load_dwordx4 v[108:111], v8, s[96:97] nt
	global_load_dwordx4 v[112:115], v9, s[96:97] nt
	global_load_dwordx4 v[116:119], v10, s[96:97] nt
	global_load_dwordx4 v[120:123], v11, s[96:97] nt
	global_load_dwordx4 v[124:127], v12, s[96:97] nt
	global_load_dwordx4 v[128:131], v13, s[96:97] nt
	ds_read2_b32 v[52:53], v15 offset0:0 offset1:33
	ds_read2_b32 v[54:55], v15 offset0:66 offset1:99
	ds_read2_b32 v[56:57], v15 offset0:132 offset1:165
	ds_read2_b32 v[58:59], v15 offset0:198 offset1:231
	ds_read2_b32 v[60:61], v15 offset0:8 offset1:41
	ds_read2_b32 v[62:63], v15 offset0:74 offset1:107
	ds_read2_b32 v[64:65], v15 offset0:140 offset1:173
	ds_read2_b32 v[66:67], v15 offset0:206 offset1:239
	ds_read2_b32 v[68:69], v15 offset0:16 offset1:49
	ds_read2_b32 v[70:71], v15 offset0:82 offset1:115
	ds_read2_b32 v[72:73], v15 offset0:148 offset1:181
	ds_read2_b32 v[74:75], v15 offset0:214 offset1:247
	ds_read2_b32 v[76:77], v15 offset0:24 offset1:57
	ds_read2_b32 v[78:79], v15 offset0:90 offset1:123
	ds_read2_b32 v[80:81], v15 offset0:156 offset1:189
	ds_read2_b32 v[82:83], v15 offset0:222 offset1:255
	s_add_u32 s95, s94, 0xc00
	s_lshr_b32 vcc_lo, s95, 7
	s_and_b32 vcc_hi, s95, 0x7f
	s_mul_i32 vcc_hi, vcc_hi, 0xac000
	s_lshl_b32 vcc_lo, vcc_lo, 7
	s_add_u32 s98, s66, 0x12d00000
	s_addc_u32 s99, s67, 0
	s_add_u32 s98, s98, vcc_hi
	s_addc_u32 s99, s99, 0
	s_add_u32 s98, s98, vcc_lo
	s_addc_u32 s99, s99, 0
	s_waitcnt lgkmcnt(0)
	v_cvt_pk_bf16_f32 v84, v52, v53
	v_cvt_pk_bf16_f32 v85, v54, v55
	v_cvt_pk_bf16_f32 v86, v56, v57
	v_cvt_pk_bf16_f32 v87, v58, v59
	v_cvt_pk_bf16_f32 v88, v60, v61
	v_cvt_pk_bf16_f32 v89, v62, v63
	v_cvt_pk_bf16_f32 v90, v64, v65
	v_cvt_pk_bf16_f32 v91, v66, v67
	v_cvt_pk_bf16_f32 v92, v68, v69
	v_cvt_pk_bf16_f32 v93, v70, v71
	v_cvt_pk_bf16_f32 v94, v72, v73
	v_cvt_pk_bf16_f32 v95, v74, v75
	v_cvt_pk_bf16_f32 v96, v76, v77
	v_cvt_pk_bf16_f32 v97, v78, v79
	v_cvt_pk_bf16_f32 v98, v80, v81
	v_cvt_pk_bf16_f32 v99, v82, v83
	global_store_dwordx4 v16, v[84:87], s[98:99] nt
	global_store_dwordx4 v17, v[88:91], s[98:99] nt
	global_store_dwordx4 v18, v[92:95], s[98:99] nt
	global_store_dwordx4 v19, v[96:99], s[98:99] nt
	s_waitcnt vmcnt(23)
	ds_write_b32 v14, v20 offset:0
	ds_write_b32 v14, v21 offset:4
	ds_write_b32 v14, v22 offset:8
	ds_write_b32 v14, v23 offset:12
	s_waitcnt vmcnt(22)
	ds_write_b32 v14, v24 offset:1056
	ds_write_b32 v14, v25 offset:1060
	ds_write_b32 v14, v26 offset:1064
	ds_write_b32 v14, v27 offset:1068
	s_waitcnt vmcnt(21)
	ds_write_b32 v14, v28 offset:2112
	ds_write_b32 v14, v29 offset:2116
	ds_write_b32 v14, v30 offset:2120
	ds_write_b32 v14, v31 offset:2124
	s_waitcnt vmcnt(20)
	ds_write_b32 v14, v32 offset:3168
	ds_write_b32 v14, v33 offset:3172
	ds_write_b32 v14, v34 offset:3176
	ds_write_b32 v14, v35 offset:3180
	s_waitcnt vmcnt(19)
	ds_write_b32 v14, v36 offset:4224
	ds_write_b32 v14, v37 offset:4228
	ds_write_b32 v14, v38 offset:4232
	ds_write_b32 v14, v39 offset:4236
	s_waitcnt vmcnt(18)
	ds_write_b32 v14, v40 offset:5280
	ds_write_b32 v14, v41 offset:5284
	ds_write_b32 v14, v42 offset:5288
	ds_write_b32 v14, v43 offset:5292
	s_waitcnt vmcnt(17)
	ds_write_b32 v14, v44 offset:6336
	ds_write_b32 v14, v45 offset:6340
	ds_write_b32 v14, v46 offset:6344
	ds_write_b32 v14, v47 offset:6348
	s_waitcnt vmcnt(16)
	ds_write_b32 v14, v48 offset:7392
	ds_write_b32 v14, v49 offset:7396
	ds_write_b32 v14, v50 offset:7400
	ds_write_b32 v14, v51 offset:7404
	s_add_u32 s95, s94, 0x1800
	s_lshr_b32 vcc_lo, s95, 7
	s_and_b32 vcc_hi, s95, 0x7f
	s_lshl_b32 vcc_lo, vcc_lo, 20
	s_lshl_b32 vcc_hi, vcc_hi, 7
	s_add_u32 s96, s100, vcc_lo
	s_addc_u32 s97, s101, 0
	s_add_u32 s96, s96, vcc_hi
	s_addc_u32 s97, s97, 0
	global_load_dwordx4 v[20:23], v6, s[96:97] nt
	global_load_dwordx4 v[24:27], v7, s[96:97] nt
	global_load_dwordx4 v[28:31], v8, s[96:97] nt
	global_load_dwordx4 v[32:35], v9, s[96:97] nt
	global_load_dwordx4 v[36:39], v10, s[96:97] nt
	global_load_dwordx4 v[40:43], v11, s[96:97] nt
	global_load_dwordx4 v[44:47], v12, s[96:97] nt
	global_load_dwordx4 v[48:51], v13, s[96:97] nt
	ds_read2_b32 v[52:53], v15 offset0:0 offset1:33
	ds_read2_b32 v[54:55], v15 offset0:66 offset1:99
	ds_read2_b32 v[56:57], v15 offset0:132 offset1:165
	ds_read2_b32 v[58:59], v15 offset0:198 offset1:231
	ds_read2_b32 v[60:61], v15 offset0:8 offset1:41
	ds_read2_b32 v[62:63], v15 offset0:74 offset1:107
	ds_read2_b32 v[64:65], v15 offset0:140 offset1:173
	ds_read2_b32 v[66:67], v15 offset0:206 offset1:239
	ds_read2_b32 v[68:69], v15 offset0:16 offset1:49
	ds_read2_b32 v[70:71], v15 offset0:82 offset1:115
	ds_read2_b32 v[72:73], v15 offset0:148 offset1:181
	ds_read2_b32 v[74:75], v15 offset0:214 offset1:247
	ds_read2_b32 v[76:77], v15 offset0:24 offset1:57
	ds_read2_b32 v[78:79], v15 offset0:90 offset1:123
	ds_read2_b32 v[80:81], v15 offset0:156 offset1:189
	ds_read2_b32 v[82:83], v15 offset0:222 offset1:255
	s_add_u32 s95, s94, 0x1000
	s_lshr_b32 vcc_lo, s95, 7
	s_and_b32 vcc_hi, s95, 0x7f
	s_mul_i32 vcc_hi, vcc_hi, 0xac000
	s_lshl_b32 vcc_lo, vcc_lo, 7
	s_add_u32 s98, s66, 0x12d00000
	s_addc_u32 s99, s67, 0
	s_add_u32 s98, s98, vcc_hi
	s_addc_u32 s99, s99, 0
	s_add_u32 s98, s98, vcc_lo
	s_addc_u32 s99, s99, 0
	s_waitcnt lgkmcnt(0)
	v_cvt_pk_bf16_f32 v84, v52, v53
	v_cvt_pk_bf16_f32 v85, v54, v55
	v_cvt_pk_bf16_f32 v86, v56, v57
	v_cvt_pk_bf16_f32 v87, v58, v59
	v_cvt_pk_bf16_f32 v88, v60, v61
	v_cvt_pk_bf16_f32 v89, v62, v63
	v_cvt_pk_bf16_f32 v90, v64, v65
	v_cvt_pk_bf16_f32 v91, v66, v67
	v_cvt_pk_bf16_f32 v92, v68, v69
	v_cvt_pk_bf16_f32 v93, v70, v71
	v_cvt_pk_bf16_f32 v94, v72, v73
	v_cvt_pk_bf16_f32 v95, v74, v75
	v_cvt_pk_bf16_f32 v96, v76, v77
	v_cvt_pk_bf16_f32 v97, v78, v79
	v_cvt_pk_bf16_f32 v98, v80, v81
	v_cvt_pk_bf16_f32 v99, v82, v83
	global_store_dwordx4 v16, v[84:87], s[98:99] nt
	global_store_dwordx4 v17, v[88:91], s[98:99] nt
	global_store_dwordx4 v18, v[92:95], s[98:99] nt
	global_store_dwordx4 v19, v[96:99], s[98:99] nt
	s_waitcnt vmcnt(23)
	ds_write_b32 v14, v100 offset:0
	ds_write_b32 v14, v101 offset:4
	ds_write_b32 v14, v102 offset:8
	ds_write_b32 v14, v103 offset:12
	s_waitcnt vmcnt(22)
	ds_write_b32 v14, v104 offset:1056
	ds_write_b32 v14, v105 offset:1060
	ds_write_b32 v14, v106 offset:1064
	ds_write_b32 v14, v107 offset:1068
	s_waitcnt vmcnt(21)
	ds_write_b32 v14, v108 offset:2112
	ds_write_b32 v14, v109 offset:2116
	ds_write_b32 v14, v110 offset:2120
	ds_write_b32 v14, v111 offset:2124
	s_waitcnt vmcnt(20)
	ds_write_b32 v14, v112 offset:3168
	ds_write_b32 v14, v113 offset:3172
	ds_write_b32 v14, v114 offset:3176
	ds_write_b32 v14, v115 offset:3180
	s_waitcnt vmcnt(19)
	ds_write_b32 v14, v116 offset:4224
	ds_write_b32 v14, v117 offset:4228
	ds_write_b32 v14, v118 offset:4232
	ds_write_b32 v14, v119 offset:4236
	s_waitcnt vmcnt(18)
	ds_write_b32 v14, v120 offset:5280
	ds_write_b32 v14, v121 offset:5284
	ds_write_b32 v14, v122 offset:5288
	ds_write_b32 v14, v123 offset:5292
	s_waitcnt vmcnt(17)
	ds_write_b32 v14, v124 offset:6336
	ds_write_b32 v14, v125 offset:6340
	ds_write_b32 v14, v126 offset:6344
	ds_write_b32 v14, v127 offset:6348
	s_waitcnt vmcnt(16)
	ds_write_b32 v14, v128 offset:7392
	ds_write_b32 v14, v129 offset:7396
	ds_write_b32 v14, v130 offset:7400
	ds_write_b32 v14, v131 offset:7404
	s_add_u32 s95, s94, 0x1c00
	s_lshr_b32 vcc_lo, s95, 7
	s_and_b32 vcc_hi, s95, 0x7f
	s_lshl_b32 vcc_lo, vcc_lo, 20
	s_lshl_b32 vcc_hi, vcc_hi, 7
	s_add_u32 s96, s100, vcc_lo
	s_addc_u32 s97, s101, 0
	s_add_u32 s96, s96, vcc_hi
	s_addc_u32 s97, s97, 0
	global_load_dwordx4 v[100:103], v6, s[96:97] nt
	global_load_dwordx4 v[104:107], v7, s[96:97] nt
	global_load_dwordx4 v[108:111], v8, s[96:97] nt
	global_load_dwordx4 v[112:115], v9, s[96:97] nt
	global_load_dwordx4 v[116:119], v10, s[96:97] nt
	global_load_dwordx4 v[120:123], v11, s[96:97] nt
	global_load_dwordx4 v[124:127], v12, s[96:97] nt
	global_load_dwordx4 v[128:131], v13, s[96:97] nt
	ds_read2_b32 v[52:53], v15 offset0:0 offset1:33
	ds_read2_b32 v[54:55], v15 offset0:66 offset1:99
	ds_read2_b32 v[56:57], v15 offset0:132 offset1:165
	ds_read2_b32 v[58:59], v15 offset0:198 offset1:231
	ds_read2_b32 v[60:61], v15 offset0:8 offset1:41
	ds_read2_b32 v[62:63], v15 offset0:74 offset1:107
	ds_read2_b32 v[64:65], v15 offset0:140 offset1:173
	ds_read2_b32 v[66:67], v15 offset0:206 offset1:239
	ds_read2_b32 v[68:69], v15 offset0:16 offset1:49
	ds_read2_b32 v[70:71], v15 offset0:82 offset1:115
	ds_read2_b32 v[72:73], v15 offset0:148 offset1:181
	ds_read2_b32 v[74:75], v15 offset0:214 offset1:247
	ds_read2_b32 v[76:77], v15 offset0:24 offset1:57
	ds_read2_b32 v[78:79], v15 offset0:90 offset1:123
	ds_read2_b32 v[80:81], v15 offset0:156 offset1:189
	ds_read2_b32 v[82:83], v15 offset0:222 offset1:255
	s_add_u32 s95, s94, 0x1400
	s_lshr_b32 vcc_lo, s95, 7
	s_and_b32 vcc_hi, s95, 0x7f
	s_mul_i32 vcc_hi, vcc_hi, 0xac000
	s_lshl_b32 vcc_lo, vcc_lo, 7
	s_add_u32 s98, s66, 0x12d00000
	s_addc_u32 s99, s67, 0
	s_add_u32 s98, s98, vcc_hi
	s_addc_u32 s99, s99, 0
	s_add_u32 s98, s98, vcc_lo
	s_addc_u32 s99, s99, 0
	s_waitcnt lgkmcnt(0)
	v_cvt_pk_bf16_f32 v84, v52, v53
	v_cvt_pk_bf16_f32 v85, v54, v55
	v_cvt_pk_bf16_f32 v86, v56, v57
	v_cvt_pk_bf16_f32 v87, v58, v59
	v_cvt_pk_bf16_f32 v88, v60, v61
	v_cvt_pk_bf16_f32 v89, v62, v63
	v_cvt_pk_bf16_f32 v90, v64, v65
	v_cvt_pk_bf16_f32 v91, v66, v67
	v_cvt_pk_bf16_f32 v92, v68, v69
	v_cvt_pk_bf16_f32 v93, v70, v71
	v_cvt_pk_bf16_f32 v94, v72, v73
	v_cvt_pk_bf16_f32 v95, v74, v75
	v_cvt_pk_bf16_f32 v96, v76, v77
	v_cvt_pk_bf16_f32 v97, v78, v79
	v_cvt_pk_bf16_f32 v98, v80, v81
	v_cvt_pk_bf16_f32 v99, v82, v83
	global_store_dwordx4 v16, v[84:87], s[98:99] nt
	global_store_dwordx4 v17, v[88:91], s[98:99] nt
	global_store_dwordx4 v18, v[92:95], s[98:99] nt
	global_store_dwordx4 v19, v[96:99], s[98:99] nt
	s_waitcnt vmcnt(23)
	ds_write_b32 v14, v20 offset:0
	ds_write_b32 v14, v21 offset:4
	ds_write_b32 v14, v22 offset:8
	ds_write_b32 v14, v23 offset:12
	s_waitcnt vmcnt(22)
	ds_write_b32 v14, v24 offset:1056
	ds_write_b32 v14, v25 offset:1060
	ds_write_b32 v14, v26 offset:1064
	ds_write_b32 v14, v27 offset:1068
	s_waitcnt vmcnt(21)
	ds_write_b32 v14, v28 offset:2112
	ds_write_b32 v14, v29 offset:2116
	ds_write_b32 v14, v30 offset:2120
	ds_write_b32 v14, v31 offset:2124
	s_waitcnt vmcnt(20)
	ds_write_b32 v14, v32 offset:3168
	ds_write_b32 v14, v33 offset:3172
	ds_write_b32 v14, v34 offset:3176
	ds_write_b32 v14, v35 offset:3180
	s_waitcnt vmcnt(19)
	ds_write_b32 v14, v36 offset:4224
	ds_write_b32 v14, v37 offset:4228
	ds_write_b32 v14, v38 offset:4232
	ds_write_b32 v14, v39 offset:4236
	s_waitcnt vmcnt(18)
	ds_write_b32 v14, v40 offset:5280
	ds_write_b32 v14, v41 offset:5284
	ds_write_b32 v14, v42 offset:5288
	ds_write_b32 v14, v43 offset:5292
	s_waitcnt vmcnt(17)
	ds_write_b32 v14, v44 offset:6336
	ds_write_b32 v14, v45 offset:6340
	ds_write_b32 v14, v46 offset:6344
	ds_write_b32 v14, v47 offset:6348
	s_waitcnt vmcnt(16)
	ds_write_b32 v14, v48 offset:7392
	ds_write_b32 v14, v49 offset:7396
	ds_write_b32 v14, v50 offset:7400
	ds_write_b32 v14, v51 offset:7404
	s_add_u32 s95, s94, 0x2000
	s_lshr_b32 vcc_lo, s95, 7
	s_and_b32 vcc_hi, s95, 0x7f
	s_lshl_b32 vcc_lo, vcc_lo, 20
	s_lshl_b32 vcc_hi, vcc_hi, 7
	s_add_u32 s96, s100, vcc_lo
	s_addc_u32 s97, s101, 0
	s_add_u32 s96, s96, vcc_hi
	s_addc_u32 s97, s97, 0
	global_load_dwordx4 v[20:23], v6, s[96:97] nt
	global_load_dwordx4 v[24:27], v7, s[96:97] nt
	global_load_dwordx4 v[28:31], v8, s[96:97] nt
	global_load_dwordx4 v[32:35], v9, s[96:97] nt
	global_load_dwordx4 v[36:39], v10, s[96:97] nt
	global_load_dwordx4 v[40:43], v11, s[96:97] nt
	global_load_dwordx4 v[44:47], v12, s[96:97] nt
	global_load_dwordx4 v[48:51], v13, s[96:97] nt
	ds_read2_b32 v[52:53], v15 offset0:0 offset1:33
	ds_read2_b32 v[54:55], v15 offset0:66 offset1:99
	ds_read2_b32 v[56:57], v15 offset0:132 offset1:165
	ds_read2_b32 v[58:59], v15 offset0:198 offset1:231
	ds_read2_b32 v[60:61], v15 offset0:8 offset1:41
	ds_read2_b32 v[62:63], v15 offset0:74 offset1:107
	ds_read2_b32 v[64:65], v15 offset0:140 offset1:173
	ds_read2_b32 v[66:67], v15 offset0:206 offset1:239
	ds_read2_b32 v[68:69], v15 offset0:16 offset1:49
	ds_read2_b32 v[70:71], v15 offset0:82 offset1:115
	ds_read2_b32 v[72:73], v15 offset0:148 offset1:181
	ds_read2_b32 v[74:75], v15 offset0:214 offset1:247
	ds_read2_b32 v[76:77], v15 offset0:24 offset1:57
	ds_read2_b32 v[78:79], v15 offset0:90 offset1:123
	ds_read2_b32 v[80:81], v15 offset0:156 offset1:189
	ds_read2_b32 v[82:83], v15 offset0:222 offset1:255
	s_add_u32 s95, s94, 0x1800
	s_lshr_b32 vcc_lo, s95, 7
	s_and_b32 vcc_hi, s95, 0x7f
	s_mul_i32 vcc_hi, vcc_hi, 0xac000
	s_lshl_b32 vcc_lo, vcc_lo, 7
	s_add_u32 s98, s66, 0x12d00000
	s_addc_u32 s99, s67, 0
	s_add_u32 s98, s98, vcc_hi
	s_addc_u32 s99, s99, 0
	s_add_u32 s98, s98, vcc_lo
	s_addc_u32 s99, s99, 0
	s_waitcnt lgkmcnt(0)
	v_cvt_pk_bf16_f32 v84, v52, v53
	v_cvt_pk_bf16_f32 v85, v54, v55
	v_cvt_pk_bf16_f32 v86, v56, v57
	v_cvt_pk_bf16_f32 v87, v58, v59
	v_cvt_pk_bf16_f32 v88, v60, v61
	v_cvt_pk_bf16_f32 v89, v62, v63
	v_cvt_pk_bf16_f32 v90, v64, v65
	v_cvt_pk_bf16_f32 v91, v66, v67
	v_cvt_pk_bf16_f32 v92, v68, v69
	v_cvt_pk_bf16_f32 v93, v70, v71
	v_cvt_pk_bf16_f32 v94, v72, v73
	v_cvt_pk_bf16_f32 v95, v74, v75
	v_cvt_pk_bf16_f32 v96, v76, v77
	v_cvt_pk_bf16_f32 v97, v78, v79
	v_cvt_pk_bf16_f32 v98, v80, v81
	v_cvt_pk_bf16_f32 v99, v82, v83
	global_store_dwordx4 v16, v[84:87], s[98:99] nt
	global_store_dwordx4 v17, v[88:91], s[98:99] nt
	global_store_dwordx4 v18, v[92:95], s[98:99] nt
	global_store_dwordx4 v19, v[96:99], s[98:99] nt
	s_waitcnt vmcnt(23)
	ds_write_b32 v14, v100 offset:0
	ds_write_b32 v14, v101 offset:4
	ds_write_b32 v14, v102 offset:8
	ds_write_b32 v14, v103 offset:12
	s_waitcnt vmcnt(22)
	ds_write_b32 v14, v104 offset:1056
	ds_write_b32 v14, v105 offset:1060
	ds_write_b32 v14, v106 offset:1064
	ds_write_b32 v14, v107 offset:1068
	s_waitcnt vmcnt(21)
	ds_write_b32 v14, v108 offset:2112
	ds_write_b32 v14, v109 offset:2116
	ds_write_b32 v14, v110 offset:2120
	ds_write_b32 v14, v111 offset:2124
	s_waitcnt vmcnt(20)
	ds_write_b32 v14, v112 offset:3168
	ds_write_b32 v14, v113 offset:3172
	ds_write_b32 v14, v114 offset:3176
	ds_write_b32 v14, v115 offset:3180
	s_waitcnt vmcnt(19)
	ds_write_b32 v14, v116 offset:4224
	ds_write_b32 v14, v117 offset:4228
	ds_write_b32 v14, v118 offset:4232
	ds_write_b32 v14, v119 offset:4236
	s_waitcnt vmcnt(18)
	ds_write_b32 v14, v120 offset:5280
	ds_write_b32 v14, v121 offset:5284
	ds_write_b32 v14, v122 offset:5288
	ds_write_b32 v14, v123 offset:5292
	s_waitcnt vmcnt(17)
	ds_write_b32 v14, v124 offset:6336
	ds_write_b32 v14, v125 offset:6340
	ds_write_b32 v14, v126 offset:6344
	ds_write_b32 v14, v127 offset:6348
	s_waitcnt vmcnt(16)
	ds_write_b32 v14, v128 offset:7392
	ds_write_b32 v14, v129 offset:7396
	ds_write_b32 v14, v130 offset:7400
	ds_write_b32 v14, v131 offset:7404
	s_add_u32 s95, s94, 0x2400
	s_lshr_b32 vcc_lo, s95, 7
	s_and_b32 vcc_hi, s95, 0x7f
	s_lshl_b32 vcc_lo, vcc_lo, 20
	s_lshl_b32 vcc_hi, vcc_hi, 7
	s_add_u32 s96, s100, vcc_lo
	s_addc_u32 s97, s101, 0
	s_add_u32 s96, s96, vcc_hi
	s_addc_u32 s97, s97, 0
	global_load_dwordx4 v[100:103], v6, s[96:97] nt
	global_load_dwordx4 v[104:107], v7, s[96:97] nt
	global_load_dwordx4 v[108:111], v8, s[96:97] nt
	global_load_dwordx4 v[112:115], v9, s[96:97] nt
	global_load_dwordx4 v[116:119], v10, s[96:97] nt
	global_load_dwordx4 v[120:123], v11, s[96:97] nt
	global_load_dwordx4 v[124:127], v12, s[96:97] nt
	global_load_dwordx4 v[128:131], v13, s[96:97] nt
	ds_read2_b32 v[52:53], v15 offset0:0 offset1:33
	ds_read2_b32 v[54:55], v15 offset0:66 offset1:99
	ds_read2_b32 v[56:57], v15 offset0:132 offset1:165
	ds_read2_b32 v[58:59], v15 offset0:198 offset1:231
	ds_read2_b32 v[60:61], v15 offset0:8 offset1:41
	ds_read2_b32 v[62:63], v15 offset0:74 offset1:107
	ds_read2_b32 v[64:65], v15 offset0:140 offset1:173
	ds_read2_b32 v[66:67], v15 offset0:206 offset1:239
	ds_read2_b32 v[68:69], v15 offset0:16 offset1:49
	ds_read2_b32 v[70:71], v15 offset0:82 offset1:115
	ds_read2_b32 v[72:73], v15 offset0:148 offset1:181
	ds_read2_b32 v[74:75], v15 offset0:214 offset1:247
	ds_read2_b32 v[76:77], v15 offset0:24 offset1:57
	ds_read2_b32 v[78:79], v15 offset0:90 offset1:123
	ds_read2_b32 v[80:81], v15 offset0:156 offset1:189
	ds_read2_b32 v[82:83], v15 offset0:222 offset1:255
	s_add_u32 s95, s94, 0x1c00
	s_lshr_b32 vcc_lo, s95, 7
	s_and_b32 vcc_hi, s95, 0x7f
	s_mul_i32 vcc_hi, vcc_hi, 0xac000
	s_lshl_b32 vcc_lo, vcc_lo, 7
	s_add_u32 s98, s66, 0x12d00000
	s_addc_u32 s99, s67, 0
	s_add_u32 s98, s98, vcc_hi
	s_addc_u32 s99, s99, 0
	s_add_u32 s98, s98, vcc_lo
	s_addc_u32 s99, s99, 0
	s_waitcnt lgkmcnt(0)
	v_cvt_pk_bf16_f32 v84, v52, v53
	v_cvt_pk_bf16_f32 v85, v54, v55
	v_cvt_pk_bf16_f32 v86, v56, v57
	v_cvt_pk_bf16_f32 v87, v58, v59
	v_cvt_pk_bf16_f32 v88, v60, v61
	v_cvt_pk_bf16_f32 v89, v62, v63
	v_cvt_pk_bf16_f32 v90, v64, v65
	v_cvt_pk_bf16_f32 v91, v66, v67
	v_cvt_pk_bf16_f32 v92, v68, v69
	v_cvt_pk_bf16_f32 v93, v70, v71
	v_cvt_pk_bf16_f32 v94, v72, v73
	v_cvt_pk_bf16_f32 v95, v74, v75
	v_cvt_pk_bf16_f32 v96, v76, v77
	v_cvt_pk_bf16_f32 v97, v78, v79
	v_cvt_pk_bf16_f32 v98, v80, v81
	v_cvt_pk_bf16_f32 v99, v82, v83
	global_store_dwordx4 v16, v[84:87], s[98:99] nt
	global_store_dwordx4 v17, v[88:91], s[98:99] nt
	global_store_dwordx4 v18, v[92:95], s[98:99] nt
	global_store_dwordx4 v19, v[96:99], s[98:99] nt
	s_waitcnt vmcnt(23)
	ds_write_b32 v14, v20 offset:0
	ds_write_b32 v14, v21 offset:4
	ds_write_b32 v14, v22 offset:8
	ds_write_b32 v14, v23 offset:12
	s_waitcnt vmcnt(22)
	ds_write_b32 v14, v24 offset:1056
	ds_write_b32 v14, v25 offset:1060
	ds_write_b32 v14, v26 offset:1064
	ds_write_b32 v14, v27 offset:1068
	s_waitcnt vmcnt(21)
	ds_write_b32 v14, v28 offset:2112
	ds_write_b32 v14, v29 offset:2116
	ds_write_b32 v14, v30 offset:2120
	ds_write_b32 v14, v31 offset:2124
	s_waitcnt vmcnt(20)
	ds_write_b32 v14, v32 offset:3168
	ds_write_b32 v14, v33 offset:3172
	ds_write_b32 v14, v34 offset:3176
	ds_write_b32 v14, v35 offset:3180
	s_waitcnt vmcnt(19)
	ds_write_b32 v14, v36 offset:4224
	ds_write_b32 v14, v37 offset:4228
	ds_write_b32 v14, v38 offset:4232
	ds_write_b32 v14, v39 offset:4236
	s_waitcnt vmcnt(18)
	ds_write_b32 v14, v40 offset:5280
	ds_write_b32 v14, v41 offset:5284
	ds_write_b32 v14, v42 offset:5288
	ds_write_b32 v14, v43 offset:5292
	s_waitcnt vmcnt(17)
	ds_write_b32 v14, v44 offset:6336
	ds_write_b32 v14, v45 offset:6340
	ds_write_b32 v14, v46 offset:6344
	ds_write_b32 v14, v47 offset:6348
	s_waitcnt vmcnt(16)
	ds_write_b32 v14, v48 offset:7392
	ds_write_b32 v14, v49 offset:7396
	ds_write_b32 v14, v50 offset:7400
	ds_write_b32 v14, v51 offset:7404
	s_add_u32 s95, s94, 0x2800
	s_lshr_b32 vcc_lo, s95, 7
	s_and_b32 vcc_hi, s95, 0x7f
	s_lshl_b32 vcc_lo, vcc_lo, 20
	s_lshl_b32 vcc_hi, vcc_hi, 7
	s_add_u32 s96, s100, vcc_lo
	s_addc_u32 s97, s101, 0
	s_add_u32 s96, s96, vcc_hi
	s_addc_u32 s97, s97, 0
	global_load_dwordx4 v[20:23], v6, s[96:97] nt
	global_load_dwordx4 v[24:27], v7, s[96:97] nt
	global_load_dwordx4 v[28:31], v8, s[96:97] nt
	global_load_dwordx4 v[32:35], v9, s[96:97] nt
	global_load_dwordx4 v[36:39], v10, s[96:97] nt
	global_load_dwordx4 v[40:43], v11, s[96:97] nt
	global_load_dwordx4 v[44:47], v12, s[96:97] nt
	global_load_dwordx4 v[48:51], v13, s[96:97] nt
	ds_read2_b32 v[52:53], v15 offset0:0 offset1:33
	ds_read2_b32 v[54:55], v15 offset0:66 offset1:99
	ds_read2_b32 v[56:57], v15 offset0:132 offset1:165
	ds_read2_b32 v[58:59], v15 offset0:198 offset1:231
	ds_read2_b32 v[60:61], v15 offset0:8 offset1:41
	ds_read2_b32 v[62:63], v15 offset0:74 offset1:107
	ds_read2_b32 v[64:65], v15 offset0:140 offset1:173
	ds_read2_b32 v[66:67], v15 offset0:206 offset1:239
	ds_read2_b32 v[68:69], v15 offset0:16 offset1:49
	ds_read2_b32 v[70:71], v15 offset0:82 offset1:115
	ds_read2_b32 v[72:73], v15 offset0:148 offset1:181
	ds_read2_b32 v[74:75], v15 offset0:214 offset1:247
	ds_read2_b32 v[76:77], v15 offset0:24 offset1:57
	ds_read2_b32 v[78:79], v15 offset0:90 offset1:123
	ds_read2_b32 v[80:81], v15 offset0:156 offset1:189
	ds_read2_b32 v[82:83], v15 offset0:222 offset1:255
	s_add_u32 s95, s94, 0x2000
	s_lshr_b32 vcc_lo, s95, 7
	s_and_b32 vcc_hi, s95, 0x7f
	s_mul_i32 vcc_hi, vcc_hi, 0xac000
	s_lshl_b32 vcc_lo, vcc_lo, 7
	s_add_u32 s98, s66, 0x12d00000
	s_addc_u32 s99, s67, 0
	s_add_u32 s98, s98, vcc_hi
	s_addc_u32 s99, s99, 0
	s_add_u32 s98, s98, vcc_lo
	s_addc_u32 s99, s99, 0
	s_waitcnt lgkmcnt(0)
	v_cvt_pk_bf16_f32 v84, v52, v53
	v_cvt_pk_bf16_f32 v85, v54, v55
	v_cvt_pk_bf16_f32 v86, v56, v57
	v_cvt_pk_bf16_f32 v87, v58, v59
	v_cvt_pk_bf16_f32 v88, v60, v61
	v_cvt_pk_bf16_f32 v89, v62, v63
	v_cvt_pk_bf16_f32 v90, v64, v65
	v_cvt_pk_bf16_f32 v91, v66, v67
	v_cvt_pk_bf16_f32 v92, v68, v69
	v_cvt_pk_bf16_f32 v93, v70, v71
	v_cvt_pk_bf16_f32 v94, v72, v73
	v_cvt_pk_bf16_f32 v95, v74, v75
	v_cvt_pk_bf16_f32 v96, v76, v77
	v_cvt_pk_bf16_f32 v97, v78, v79
	v_cvt_pk_bf16_f32 v98, v80, v81
	v_cvt_pk_bf16_f32 v99, v82, v83
	global_store_dwordx4 v16, v[84:87], s[98:99] nt
	global_store_dwordx4 v17, v[88:91], s[98:99] nt
	global_store_dwordx4 v18, v[92:95], s[98:99] nt
	global_store_dwordx4 v19, v[96:99], s[98:99] nt
	s_waitcnt vmcnt(23)
	ds_write_b32 v14, v100 offset:0
	ds_write_b32 v14, v101 offset:4
	ds_write_b32 v14, v102 offset:8
	ds_write_b32 v14, v103 offset:12
	s_waitcnt vmcnt(22)
	ds_write_b32 v14, v104 offset:1056
	ds_write_b32 v14, v105 offset:1060
	ds_write_b32 v14, v106 offset:1064
	ds_write_b32 v14, v107 offset:1068
	s_waitcnt vmcnt(21)
	ds_write_b32 v14, v108 offset:2112
	ds_write_b32 v14, v109 offset:2116
	ds_write_b32 v14, v110 offset:2120
	ds_write_b32 v14, v111 offset:2124
	s_waitcnt vmcnt(20)
	ds_write_b32 v14, v112 offset:3168
	ds_write_b32 v14, v113 offset:3172
	ds_write_b32 v14, v114 offset:3176
	ds_write_b32 v14, v115 offset:3180
	s_waitcnt vmcnt(19)
	ds_write_b32 v14, v116 offset:4224
	ds_write_b32 v14, v117 offset:4228
	ds_write_b32 v14, v118 offset:4232
	ds_write_b32 v14, v119 offset:4236
	s_waitcnt vmcnt(18)
	ds_write_b32 v14, v120 offset:5280
	ds_write_b32 v14, v121 offset:5284
	ds_write_b32 v14, v122 offset:5288
	ds_write_b32 v14, v123 offset:5292
	s_waitcnt vmcnt(17)
	ds_write_b32 v14, v124 offset:6336
	ds_write_b32 v14, v125 offset:6340
	ds_write_b32 v14, v126 offset:6344
	ds_write_b32 v14, v127 offset:6348
	s_waitcnt vmcnt(16)
	ds_write_b32 v14, v128 offset:7392
	ds_write_b32 v14, v129 offset:7396
	ds_write_b32 v14, v130 offset:7400
	ds_write_b32 v14, v131 offset:7404
	s_add_u32 s95, s94, 0x2c00
	s_lshr_b32 vcc_lo, s95, 7
	s_and_b32 vcc_hi, s95, 0x7f
	s_lshl_b32 vcc_lo, vcc_lo, 20
	s_lshl_b32 vcc_hi, vcc_hi, 7
	s_add_u32 s96, s100, vcc_lo
	s_addc_u32 s97, s101, 0
	s_add_u32 s96, s96, vcc_hi
	s_addc_u32 s97, s97, 0
	global_load_dwordx4 v[100:103], v6, s[96:97] nt
	global_load_dwordx4 v[104:107], v7, s[96:97] nt
	global_load_dwordx4 v[108:111], v8, s[96:97] nt
	global_load_dwordx4 v[112:115], v9, s[96:97] nt
	global_load_dwordx4 v[116:119], v10, s[96:97] nt
	global_load_dwordx4 v[120:123], v11, s[96:97] nt
	global_load_dwordx4 v[124:127], v12, s[96:97] nt
	global_load_dwordx4 v[128:131], v13, s[96:97] nt
	ds_read2_b32 v[52:53], v15 offset0:0 offset1:33
	ds_read2_b32 v[54:55], v15 offset0:66 offset1:99
	ds_read2_b32 v[56:57], v15 offset0:132 offset1:165
	ds_read2_b32 v[58:59], v15 offset0:198 offset1:231
	ds_read2_b32 v[60:61], v15 offset0:8 offset1:41
	ds_read2_b32 v[62:63], v15 offset0:74 offset1:107
	ds_read2_b32 v[64:65], v15 offset0:140 offset1:173
	ds_read2_b32 v[66:67], v15 offset0:206 offset1:239
	ds_read2_b32 v[68:69], v15 offset0:16 offset1:49
	ds_read2_b32 v[70:71], v15 offset0:82 offset1:115
	ds_read2_b32 v[72:73], v15 offset0:148 offset1:181
	ds_read2_b32 v[74:75], v15 offset0:214 offset1:247
	ds_read2_b32 v[76:77], v15 offset0:24 offset1:57
	ds_read2_b32 v[78:79], v15 offset0:90 offset1:123
	ds_read2_b32 v[80:81], v15 offset0:156 offset1:189
	ds_read2_b32 v[82:83], v15 offset0:222 offset1:255
	s_add_u32 s95, s94, 0x2400
	s_lshr_b32 vcc_lo, s95, 7
	s_and_b32 vcc_hi, s95, 0x7f
	s_mul_i32 vcc_hi, vcc_hi, 0xac000
	s_lshl_b32 vcc_lo, vcc_lo, 7
	s_add_u32 s98, s66, 0x12d00000
	s_addc_u32 s99, s67, 0
	s_add_u32 s98, s98, vcc_hi
	s_addc_u32 s99, s99, 0
	s_add_u32 s98, s98, vcc_lo
	s_addc_u32 s99, s99, 0
	s_waitcnt lgkmcnt(0)
	v_cvt_pk_bf16_f32 v84, v52, v53
	v_cvt_pk_bf16_f32 v85, v54, v55
	v_cvt_pk_bf16_f32 v86, v56, v57
	v_cvt_pk_bf16_f32 v87, v58, v59
	v_cvt_pk_bf16_f32 v88, v60, v61
	v_cvt_pk_bf16_f32 v89, v62, v63
	v_cvt_pk_bf16_f32 v90, v64, v65
	v_cvt_pk_bf16_f32 v91, v66, v67
	v_cvt_pk_bf16_f32 v92, v68, v69
	v_cvt_pk_bf16_f32 v93, v70, v71
	v_cvt_pk_bf16_f32 v94, v72, v73
	v_cvt_pk_bf16_f32 v95, v74, v75
	v_cvt_pk_bf16_f32 v96, v76, v77
	v_cvt_pk_bf16_f32 v97, v78, v79
	v_cvt_pk_bf16_f32 v98, v80, v81
	v_cvt_pk_bf16_f32 v99, v82, v83
	global_store_dwordx4 v16, v[84:87], s[98:99] nt
	global_store_dwordx4 v17, v[88:91], s[98:99] nt
	global_store_dwordx4 v18, v[92:95], s[98:99] nt
	global_store_dwordx4 v19, v[96:99], s[98:99] nt
	s_waitcnt vmcnt(23)
	ds_write_b32 v14, v20 offset:0
	ds_write_b32 v14, v21 offset:4
	ds_write_b32 v14, v22 offset:8
	ds_write_b32 v14, v23 offset:12
	s_waitcnt vmcnt(22)
	ds_write_b32 v14, v24 offset:1056
	ds_write_b32 v14, v25 offset:1060
	ds_write_b32 v14, v26 offset:1064
	ds_write_b32 v14, v27 offset:1068
	s_waitcnt vmcnt(21)
	ds_write_b32 v14, v28 offset:2112
	ds_write_b32 v14, v29 offset:2116
	ds_write_b32 v14, v30 offset:2120
	ds_write_b32 v14, v31 offset:2124
	s_waitcnt vmcnt(20)
	ds_write_b32 v14, v32 offset:3168
	ds_write_b32 v14, v33 offset:3172
	ds_write_b32 v14, v34 offset:3176
	ds_write_b32 v14, v35 offset:3180
	s_waitcnt vmcnt(19)
	ds_write_b32 v14, v36 offset:4224
	ds_write_b32 v14, v37 offset:4228
	ds_write_b32 v14, v38 offset:4232
	ds_write_b32 v14, v39 offset:4236
	s_waitcnt vmcnt(18)
	ds_write_b32 v14, v40 offset:5280
	ds_write_b32 v14, v41 offset:5284
	ds_write_b32 v14, v42 offset:5288
	ds_write_b32 v14, v43 offset:5292
	s_waitcnt vmcnt(17)
	ds_write_b32 v14, v44 offset:6336
	ds_write_b32 v14, v45 offset:6340
	ds_write_b32 v14, v46 offset:6344
	ds_write_b32 v14, v47 offset:6348
	s_waitcnt vmcnt(16)
	ds_write_b32 v14, v48 offset:7392
	ds_write_b32 v14, v49 offset:7396
	ds_write_b32 v14, v50 offset:7400
	ds_write_b32 v14, v51 offset:7404
	s_add_u32 s95, s94, 0x3000
	s_lshr_b32 vcc_lo, s95, 7
	s_and_b32 vcc_hi, s95, 0x7f
	s_lshl_b32 vcc_lo, vcc_lo, 20
	s_lshl_b32 vcc_hi, vcc_hi, 7
	s_add_u32 s96, s100, vcc_lo
	s_addc_u32 s97, s101, 0
	s_add_u32 s96, s96, vcc_hi
	s_addc_u32 s97, s97, 0
	global_load_dwordx4 v[20:23], v6, s[96:97] nt
	global_load_dwordx4 v[24:27], v7, s[96:97] nt
	global_load_dwordx4 v[28:31], v8, s[96:97] nt
	global_load_dwordx4 v[32:35], v9, s[96:97] nt
	global_load_dwordx4 v[36:39], v10, s[96:97] nt
	global_load_dwordx4 v[40:43], v11, s[96:97] nt
	global_load_dwordx4 v[44:47], v12, s[96:97] nt
	global_load_dwordx4 v[48:51], v13, s[96:97] nt
	ds_read2_b32 v[52:53], v15 offset0:0 offset1:33
	ds_read2_b32 v[54:55], v15 offset0:66 offset1:99
	ds_read2_b32 v[56:57], v15 offset0:132 offset1:165
	ds_read2_b32 v[58:59], v15 offset0:198 offset1:231
	ds_read2_b32 v[60:61], v15 offset0:8 offset1:41
	ds_read2_b32 v[62:63], v15 offset0:74 offset1:107
	ds_read2_b32 v[64:65], v15 offset0:140 offset1:173
	ds_read2_b32 v[66:67], v15 offset0:206 offset1:239
	ds_read2_b32 v[68:69], v15 offset0:16 offset1:49
	ds_read2_b32 v[70:71], v15 offset0:82 offset1:115
	ds_read2_b32 v[72:73], v15 offset0:148 offset1:181
	ds_read2_b32 v[74:75], v15 offset0:214 offset1:247
	ds_read2_b32 v[76:77], v15 offset0:24 offset1:57
	ds_read2_b32 v[78:79], v15 offset0:90 offset1:123
	ds_read2_b32 v[80:81], v15 offset0:156 offset1:189
	ds_read2_b32 v[82:83], v15 offset0:222 offset1:255
	s_add_u32 s95, s94, 0x2800
	s_lshr_b32 vcc_lo, s95, 7
	s_and_b32 vcc_hi, s95, 0x7f
	s_mul_i32 vcc_hi, vcc_hi, 0xac000
	s_lshl_b32 vcc_lo, vcc_lo, 7
	s_add_u32 s98, s66, 0x12d00000
	s_addc_u32 s99, s67, 0
	s_add_u32 s98, s98, vcc_hi
	s_addc_u32 s99, s99, 0
	s_add_u32 s98, s98, vcc_lo
	s_addc_u32 s99, s99, 0
	s_waitcnt lgkmcnt(0)
	v_cvt_pk_bf16_f32 v84, v52, v53
	v_cvt_pk_bf16_f32 v85, v54, v55
	v_cvt_pk_bf16_f32 v86, v56, v57
	v_cvt_pk_bf16_f32 v87, v58, v59
	v_cvt_pk_bf16_f32 v88, v60, v61
	v_cvt_pk_bf16_f32 v89, v62, v63
	v_cvt_pk_bf16_f32 v90, v64, v65
	v_cvt_pk_bf16_f32 v91, v66, v67
	v_cvt_pk_bf16_f32 v92, v68, v69
	v_cvt_pk_bf16_f32 v93, v70, v71
	v_cvt_pk_bf16_f32 v94, v72, v73
	v_cvt_pk_bf16_f32 v95, v74, v75
	v_cvt_pk_bf16_f32 v96, v76, v77
	v_cvt_pk_bf16_f32 v97, v78, v79
	v_cvt_pk_bf16_f32 v98, v80, v81
	v_cvt_pk_bf16_f32 v99, v82, v83
	global_store_dwordx4 v16, v[84:87], s[98:99] nt
	global_store_dwordx4 v17, v[88:91], s[98:99] nt
	global_store_dwordx4 v18, v[92:95], s[98:99] nt
	global_store_dwordx4 v19, v[96:99], s[98:99] nt
	s_waitcnt vmcnt(23)
	ds_write_b32 v14, v100 offset:0
	ds_write_b32 v14, v101 offset:4
	ds_write_b32 v14, v102 offset:8
	ds_write_b32 v14, v103 offset:12
	s_waitcnt vmcnt(22)
	ds_write_b32 v14, v104 offset:1056
	ds_write_b32 v14, v105 offset:1060
	ds_write_b32 v14, v106 offset:1064
	ds_write_b32 v14, v107 offset:1068
	s_waitcnt vmcnt(21)
	ds_write_b32 v14, v108 offset:2112
	ds_write_b32 v14, v109 offset:2116
	ds_write_b32 v14, v110 offset:2120
	ds_write_b32 v14, v111 offset:2124
	s_waitcnt vmcnt(20)
	ds_write_b32 v14, v112 offset:3168
	ds_write_b32 v14, v113 offset:3172
	ds_write_b32 v14, v114 offset:3176
	ds_write_b32 v14, v115 offset:3180
	s_waitcnt vmcnt(19)
	ds_write_b32 v14, v116 offset:4224
	ds_write_b32 v14, v117 offset:4228
	ds_write_b32 v14, v118 offset:4232
	ds_write_b32 v14, v119 offset:4236
	s_waitcnt vmcnt(18)
	ds_write_b32 v14, v120 offset:5280
	ds_write_b32 v14, v121 offset:5284
	ds_write_b32 v14, v122 offset:5288
	ds_write_b32 v14, v123 offset:5292
	s_waitcnt vmcnt(17)
	ds_write_b32 v14, v124 offset:6336
	ds_write_b32 v14, v125 offset:6340
	ds_write_b32 v14, v126 offset:6344
	ds_write_b32 v14, v127 offset:6348
	s_waitcnt vmcnt(16)
	ds_write_b32 v14, v128 offset:7392
	ds_write_b32 v14, v129 offset:7396
	ds_write_b32 v14, v130 offset:7400
	ds_write_b32 v14, v131 offset:7404
	s_add_u32 s95, s94, 0x3400
	s_lshr_b32 vcc_lo, s95, 7
	s_and_b32 vcc_hi, s95, 0x7f
	s_lshl_b32 vcc_lo, vcc_lo, 20
	s_lshl_b32 vcc_hi, vcc_hi, 7
	s_add_u32 s96, s100, vcc_lo
	s_addc_u32 s97, s101, 0
	s_add_u32 s96, s96, vcc_hi
	s_addc_u32 s97, s97, 0
	global_load_dwordx4 v[100:103], v6, s[96:97] nt
	global_load_dwordx4 v[104:107], v7, s[96:97] nt
	global_load_dwordx4 v[108:111], v8, s[96:97] nt
	global_load_dwordx4 v[112:115], v9, s[96:97] nt
	global_load_dwordx4 v[116:119], v10, s[96:97] nt
	global_load_dwordx4 v[120:123], v11, s[96:97] nt
	global_load_dwordx4 v[124:127], v12, s[96:97] nt
	global_load_dwordx4 v[128:131], v13, s[96:97] nt
	ds_read2_b32 v[52:53], v15 offset0:0 offset1:33
	ds_read2_b32 v[54:55], v15 offset0:66 offset1:99
	ds_read2_b32 v[56:57], v15 offset0:132 offset1:165
	ds_read2_b32 v[58:59], v15 offset0:198 offset1:231
	ds_read2_b32 v[60:61], v15 offset0:8 offset1:41
	ds_read2_b32 v[62:63], v15 offset0:74 offset1:107
	ds_read2_b32 v[64:65], v15 offset0:140 offset1:173
	ds_read2_b32 v[66:67], v15 offset0:206 offset1:239
	ds_read2_b32 v[68:69], v15 offset0:16 offset1:49
	ds_read2_b32 v[70:71], v15 offset0:82 offset1:115
	ds_read2_b32 v[72:73], v15 offset0:148 offset1:181
	ds_read2_b32 v[74:75], v15 offset0:214 offset1:247
	ds_read2_b32 v[76:77], v15 offset0:24 offset1:57
	ds_read2_b32 v[78:79], v15 offset0:90 offset1:123
	ds_read2_b32 v[80:81], v15 offset0:156 offset1:189
	ds_read2_b32 v[82:83], v15 offset0:222 offset1:255
	s_add_u32 s95, s94, 0x2c00
	s_lshr_b32 vcc_lo, s95, 7
	s_and_b32 vcc_hi, s95, 0x7f
	s_mul_i32 vcc_hi, vcc_hi, 0xac000
	s_lshl_b32 vcc_lo, vcc_lo, 7
	s_add_u32 s98, s66, 0x12d00000
	s_addc_u32 s99, s67, 0
	s_add_u32 s98, s98, vcc_hi
	s_addc_u32 s99, s99, 0
	s_add_u32 s98, s98, vcc_lo
	s_addc_u32 s99, s99, 0
	s_waitcnt lgkmcnt(0)
	v_cvt_pk_bf16_f32 v84, v52, v53
	v_cvt_pk_bf16_f32 v85, v54, v55
	v_cvt_pk_bf16_f32 v86, v56, v57
	v_cvt_pk_bf16_f32 v87, v58, v59
	v_cvt_pk_bf16_f32 v88, v60, v61
	v_cvt_pk_bf16_f32 v89, v62, v63
	v_cvt_pk_bf16_f32 v90, v64, v65
	v_cvt_pk_bf16_f32 v91, v66, v67
	v_cvt_pk_bf16_f32 v92, v68, v69
	v_cvt_pk_bf16_f32 v93, v70, v71
	v_cvt_pk_bf16_f32 v94, v72, v73
	v_cvt_pk_bf16_f32 v95, v74, v75
	v_cvt_pk_bf16_f32 v96, v76, v77
	v_cvt_pk_bf16_f32 v97, v78, v79
	v_cvt_pk_bf16_f32 v98, v80, v81
	v_cvt_pk_bf16_f32 v99, v82, v83
	global_store_dwordx4 v16, v[84:87], s[98:99] nt
	global_store_dwordx4 v17, v[88:91], s[98:99] nt
	global_store_dwordx4 v18, v[92:95], s[98:99] nt
	global_store_dwordx4 v19, v[96:99], s[98:99] nt
	s_waitcnt vmcnt(23)
	ds_write_b32 v14, v20 offset:0
	ds_write_b32 v14, v21 offset:4
	ds_write_b32 v14, v22 offset:8
	ds_write_b32 v14, v23 offset:12
	s_waitcnt vmcnt(22)
	ds_write_b32 v14, v24 offset:1056
	ds_write_b32 v14, v25 offset:1060
	ds_write_b32 v14, v26 offset:1064
	ds_write_b32 v14, v27 offset:1068
	s_waitcnt vmcnt(21)
	ds_write_b32 v14, v28 offset:2112
	ds_write_b32 v14, v29 offset:2116
	ds_write_b32 v14, v30 offset:2120
	ds_write_b32 v14, v31 offset:2124
	s_waitcnt vmcnt(20)
	ds_write_b32 v14, v32 offset:3168
	ds_write_b32 v14, v33 offset:3172
	ds_write_b32 v14, v34 offset:3176
	ds_write_b32 v14, v35 offset:3180
	s_waitcnt vmcnt(19)
	ds_write_b32 v14, v36 offset:4224
	ds_write_b32 v14, v37 offset:4228
	ds_write_b32 v14, v38 offset:4232
	ds_write_b32 v14, v39 offset:4236
	s_waitcnt vmcnt(18)
	ds_write_b32 v14, v40 offset:5280
	ds_write_b32 v14, v41 offset:5284
	ds_write_b32 v14, v42 offset:5288
	ds_write_b32 v14, v43 offset:5292
	s_waitcnt vmcnt(17)
	ds_write_b32 v14, v44 offset:6336
	ds_write_b32 v14, v45 offset:6340
	ds_write_b32 v14, v46 offset:6344
	ds_write_b32 v14, v47 offset:6348
	s_waitcnt vmcnt(16)
	ds_write_b32 v14, v48 offset:7392
	ds_write_b32 v14, v49 offset:7396
	ds_write_b32 v14, v50 offset:7400
	ds_write_b32 v14, v51 offset:7404
	s_add_u32 s95, s94, 0x3800
	s_lshr_b32 vcc_lo, s95, 7
	s_and_b32 vcc_hi, s95, 0x7f
	s_lshl_b32 vcc_lo, vcc_lo, 20
	s_lshl_b32 vcc_hi, vcc_hi, 7
	s_add_u32 s96, s100, vcc_lo
	s_addc_u32 s97, s101, 0
	s_add_u32 s96, s96, vcc_hi
	s_addc_u32 s97, s97, 0
	global_load_dwordx4 v[20:23], v6, s[96:97] nt
	global_load_dwordx4 v[24:27], v7, s[96:97] nt
	global_load_dwordx4 v[28:31], v8, s[96:97] nt
	global_load_dwordx4 v[32:35], v9, s[96:97] nt
	global_load_dwordx4 v[36:39], v10, s[96:97] nt
	global_load_dwordx4 v[40:43], v11, s[96:97] nt
	global_load_dwordx4 v[44:47], v12, s[96:97] nt
	global_load_dwordx4 v[48:51], v13, s[96:97] nt
	ds_read2_b32 v[52:53], v15 offset0:0 offset1:33
	ds_read2_b32 v[54:55], v15 offset0:66 offset1:99
	ds_read2_b32 v[56:57], v15 offset0:132 offset1:165
	ds_read2_b32 v[58:59], v15 offset0:198 offset1:231
	ds_read2_b32 v[60:61], v15 offset0:8 offset1:41
	ds_read2_b32 v[62:63], v15 offset0:74 offset1:107
	ds_read2_b32 v[64:65], v15 offset0:140 offset1:173
	ds_read2_b32 v[66:67], v15 offset0:206 offset1:239
	ds_read2_b32 v[68:69], v15 offset0:16 offset1:49
	ds_read2_b32 v[70:71], v15 offset0:82 offset1:115
	ds_read2_b32 v[72:73], v15 offset0:148 offset1:181
	ds_read2_b32 v[74:75], v15 offset0:214 offset1:247
	ds_read2_b32 v[76:77], v15 offset0:24 offset1:57
	ds_read2_b32 v[78:79], v15 offset0:90 offset1:123
	ds_read2_b32 v[80:81], v15 offset0:156 offset1:189
	ds_read2_b32 v[82:83], v15 offset0:222 offset1:255
	s_add_u32 s95, s94, 0x3000
	s_lshr_b32 vcc_lo, s95, 7
	s_and_b32 vcc_hi, s95, 0x7f
	s_mul_i32 vcc_hi, vcc_hi, 0xac000
	s_lshl_b32 vcc_lo, vcc_lo, 7
	s_add_u32 s98, s66, 0x12d00000
	s_addc_u32 s99, s67, 0
	s_add_u32 s98, s98, vcc_hi
	s_addc_u32 s99, s99, 0
	s_add_u32 s98, s98, vcc_lo
	s_addc_u32 s99, s99, 0
	s_waitcnt lgkmcnt(0)
	v_cvt_pk_bf16_f32 v84, v52, v53
	v_cvt_pk_bf16_f32 v85, v54, v55
	v_cvt_pk_bf16_f32 v86, v56, v57
	v_cvt_pk_bf16_f32 v87, v58, v59
	v_cvt_pk_bf16_f32 v88, v60, v61
	v_cvt_pk_bf16_f32 v89, v62, v63
	v_cvt_pk_bf16_f32 v90, v64, v65
	v_cvt_pk_bf16_f32 v91, v66, v67
	v_cvt_pk_bf16_f32 v92, v68, v69
	v_cvt_pk_bf16_f32 v93, v70, v71
	v_cvt_pk_bf16_f32 v94, v72, v73
	v_cvt_pk_bf16_f32 v95, v74, v75
	v_cvt_pk_bf16_f32 v96, v76, v77
	v_cvt_pk_bf16_f32 v97, v78, v79
	v_cvt_pk_bf16_f32 v98, v80, v81
	v_cvt_pk_bf16_f32 v99, v82, v83
	global_store_dwordx4 v16, v[84:87], s[98:99] nt
	global_store_dwordx4 v17, v[88:91], s[98:99] nt
	global_store_dwordx4 v18, v[92:95], s[98:99] nt
	global_store_dwordx4 v19, v[96:99], s[98:99] nt
	s_waitcnt vmcnt(23)
	ds_write_b32 v14, v100 offset:0
	ds_write_b32 v14, v101 offset:4
	ds_write_b32 v14, v102 offset:8
	ds_write_b32 v14, v103 offset:12
	s_waitcnt vmcnt(22)
	ds_write_b32 v14, v104 offset:1056
	ds_write_b32 v14, v105 offset:1060
	ds_write_b32 v14, v106 offset:1064
	ds_write_b32 v14, v107 offset:1068
	s_waitcnt vmcnt(21)
	ds_write_b32 v14, v108 offset:2112
	ds_write_b32 v14, v109 offset:2116
	ds_write_b32 v14, v110 offset:2120
	ds_write_b32 v14, v111 offset:2124
	s_waitcnt vmcnt(20)
	ds_write_b32 v14, v112 offset:3168
	ds_write_b32 v14, v113 offset:3172
	ds_write_b32 v14, v114 offset:3176
	ds_write_b32 v14, v115 offset:3180
	s_waitcnt vmcnt(19)
	ds_write_b32 v14, v116 offset:4224
	ds_write_b32 v14, v117 offset:4228
	ds_write_b32 v14, v118 offset:4232
	ds_write_b32 v14, v119 offset:4236
	s_waitcnt vmcnt(18)
	ds_write_b32 v14, v120 offset:5280
	ds_write_b32 v14, v121 offset:5284
	ds_write_b32 v14, v122 offset:5288
	ds_write_b32 v14, v123 offset:5292
	s_waitcnt vmcnt(17)
	ds_write_b32 v14, v124 offset:6336
	ds_write_b32 v14, v125 offset:6340
	ds_write_b32 v14, v126 offset:6344
	ds_write_b32 v14, v127 offset:6348
	s_waitcnt vmcnt(16)
	ds_write_b32 v14, v128 offset:7392
	ds_write_b32 v14, v129 offset:7396
	ds_write_b32 v14, v130 offset:7400
	ds_write_b32 v14, v131 offset:7404
	s_add_u32 s95, s94, 0x3c00
	s_lshr_b32 vcc_lo, s95, 7
	s_and_b32 vcc_hi, s95, 0x7f
	s_lshl_b32 vcc_lo, vcc_lo, 20
	s_lshl_b32 vcc_hi, vcc_hi, 7
	s_add_u32 s96, s100, vcc_lo
	s_addc_u32 s97, s101, 0
	s_add_u32 s96, s96, vcc_hi
	s_addc_u32 s97, s97, 0
	global_load_dwordx4 v[100:103], v6, s[96:97] nt
	global_load_dwordx4 v[104:107], v7, s[96:97] nt
	global_load_dwordx4 v[108:111], v8, s[96:97] nt
	global_load_dwordx4 v[112:115], v9, s[96:97] nt
	global_load_dwordx4 v[116:119], v10, s[96:97] nt
	global_load_dwordx4 v[120:123], v11, s[96:97] nt
	global_load_dwordx4 v[124:127], v12, s[96:97] nt
	global_load_dwordx4 v[128:131], v13, s[96:97] nt
	ds_read2_b32 v[52:53], v15 offset0:0 offset1:33
	ds_read2_b32 v[54:55], v15 offset0:66 offset1:99
	ds_read2_b32 v[56:57], v15 offset0:132 offset1:165
	ds_read2_b32 v[58:59], v15 offset0:198 offset1:231
	ds_read2_b32 v[60:61], v15 offset0:8 offset1:41
	ds_read2_b32 v[62:63], v15 offset0:74 offset1:107
	ds_read2_b32 v[64:65], v15 offset0:140 offset1:173
	ds_read2_b32 v[66:67], v15 offset0:206 offset1:239
	ds_read2_b32 v[68:69], v15 offset0:16 offset1:49
	ds_read2_b32 v[70:71], v15 offset0:82 offset1:115
	ds_read2_b32 v[72:73], v15 offset0:148 offset1:181
	ds_read2_b32 v[74:75], v15 offset0:214 offset1:247
	ds_read2_b32 v[76:77], v15 offset0:24 offset1:57
	ds_read2_b32 v[78:79], v15 offset0:90 offset1:123
	ds_read2_b32 v[80:81], v15 offset0:156 offset1:189
	ds_read2_b32 v[82:83], v15 offset0:222 offset1:255
	s_add_u32 s95, s94, 0x3400
	s_lshr_b32 vcc_lo, s95, 7
	s_and_b32 vcc_hi, s95, 0x7f
	s_mul_i32 vcc_hi, vcc_hi, 0xac000
	s_lshl_b32 vcc_lo, vcc_lo, 7
	s_add_u32 s98, s66, 0x12d00000
	s_addc_u32 s99, s67, 0
	s_add_u32 s98, s98, vcc_hi
	s_addc_u32 s99, s99, 0
	s_add_u32 s98, s98, vcc_lo
	s_addc_u32 s99, s99, 0
	s_waitcnt lgkmcnt(0)
	v_cvt_pk_bf16_f32 v84, v52, v53
	v_cvt_pk_bf16_f32 v85, v54, v55
	v_cvt_pk_bf16_f32 v86, v56, v57
	v_cvt_pk_bf16_f32 v87, v58, v59
	v_cvt_pk_bf16_f32 v88, v60, v61
	v_cvt_pk_bf16_f32 v89, v62, v63
	v_cvt_pk_bf16_f32 v90, v64, v65
	v_cvt_pk_bf16_f32 v91, v66, v67
	v_cvt_pk_bf16_f32 v92, v68, v69
	v_cvt_pk_bf16_f32 v93, v70, v71
	v_cvt_pk_bf16_f32 v94, v72, v73
	v_cvt_pk_bf16_f32 v95, v74, v75
	v_cvt_pk_bf16_f32 v96, v76, v77
	v_cvt_pk_bf16_f32 v97, v78, v79
	v_cvt_pk_bf16_f32 v98, v80, v81
	v_cvt_pk_bf16_f32 v99, v82, v83
	global_store_dwordx4 v16, v[84:87], s[98:99] nt
	global_store_dwordx4 v17, v[88:91], s[98:99] nt
	global_store_dwordx4 v18, v[92:95], s[98:99] nt
	global_store_dwordx4 v19, v[96:99], s[98:99] nt
	s_waitcnt vmcnt(23)
	ds_write_b32 v14, v20 offset:0
	ds_write_b32 v14, v21 offset:4
	ds_write_b32 v14, v22 offset:8
	ds_write_b32 v14, v23 offset:12
	s_waitcnt vmcnt(22)
	ds_write_b32 v14, v24 offset:1056
	ds_write_b32 v14, v25 offset:1060
	ds_write_b32 v14, v26 offset:1064
	ds_write_b32 v14, v27 offset:1068
	s_waitcnt vmcnt(21)
	ds_write_b32 v14, v28 offset:2112
	ds_write_b32 v14, v29 offset:2116
	ds_write_b32 v14, v30 offset:2120
	ds_write_b32 v14, v31 offset:2124
	s_waitcnt vmcnt(20)
	ds_write_b32 v14, v32 offset:3168
	ds_write_b32 v14, v33 offset:3172
	ds_write_b32 v14, v34 offset:3176
	ds_write_b32 v14, v35 offset:3180
	s_waitcnt vmcnt(19)
	ds_write_b32 v14, v36 offset:4224
	ds_write_b32 v14, v37 offset:4228
	ds_write_b32 v14, v38 offset:4232
	ds_write_b32 v14, v39 offset:4236
	s_waitcnt vmcnt(18)
	ds_write_b32 v14, v40 offset:5280
	ds_write_b32 v14, v41 offset:5284
	ds_write_b32 v14, v42 offset:5288
	ds_write_b32 v14, v43 offset:5292
	s_waitcnt vmcnt(17)
	ds_write_b32 v14, v44 offset:6336
	ds_write_b32 v14, v45 offset:6340
	ds_write_b32 v14, v46 offset:6344
	ds_write_b32 v14, v47 offset:6348
	s_waitcnt vmcnt(16)
	ds_write_b32 v14, v48 offset:7392
	ds_write_b32 v14, v49 offset:7396
	ds_write_b32 v14, v50 offset:7400
	ds_write_b32 v14, v51 offset:7404
	s_add_u32 s95, s94, 0x4000
	s_lshr_b32 vcc_lo, s95, 7
	s_and_b32 vcc_hi, s95, 0x7f
	s_lshl_b32 vcc_lo, vcc_lo, 20
	s_lshl_b32 vcc_hi, vcc_hi, 7
	s_add_u32 s96, s100, vcc_lo
	s_addc_u32 s97, s101, 0
	s_add_u32 s96, s96, vcc_hi
	s_addc_u32 s97, s97, 0
	global_load_dwordx4 v[20:23], v6, s[96:97] nt
	global_load_dwordx4 v[24:27], v7, s[96:97] nt
	global_load_dwordx4 v[28:31], v8, s[96:97] nt
	global_load_dwordx4 v[32:35], v9, s[96:97] nt
	global_load_dwordx4 v[36:39], v10, s[96:97] nt
	global_load_dwordx4 v[40:43], v11, s[96:97] nt
	global_load_dwordx4 v[44:47], v12, s[96:97] nt
	global_load_dwordx4 v[48:51], v13, s[96:97] nt
	ds_read2_b32 v[52:53], v15 offset0:0 offset1:33
	ds_read2_b32 v[54:55], v15 offset0:66 offset1:99
	ds_read2_b32 v[56:57], v15 offset0:132 offset1:165
	ds_read2_b32 v[58:59], v15 offset0:198 offset1:231
	ds_read2_b32 v[60:61], v15 offset0:8 offset1:41
	ds_read2_b32 v[62:63], v15 offset0:74 offset1:107
	ds_read2_b32 v[64:65], v15 offset0:140 offset1:173
	ds_read2_b32 v[66:67], v15 offset0:206 offset1:239
	ds_read2_b32 v[68:69], v15 offset0:16 offset1:49
	ds_read2_b32 v[70:71], v15 offset0:82 offset1:115
	ds_read2_b32 v[72:73], v15 offset0:148 offset1:181
	ds_read2_b32 v[74:75], v15 offset0:214 offset1:247
	ds_read2_b32 v[76:77], v15 offset0:24 offset1:57
	ds_read2_b32 v[78:79], v15 offset0:90 offset1:123
	ds_read2_b32 v[80:81], v15 offset0:156 offset1:189
	ds_read2_b32 v[82:83], v15 offset0:222 offset1:255
	s_add_u32 s95, s94, 0x3800
	s_lshr_b32 vcc_lo, s95, 7
	s_and_b32 vcc_hi, s95, 0x7f
	s_mul_i32 vcc_hi, vcc_hi, 0xac000
	s_lshl_b32 vcc_lo, vcc_lo, 7
	s_add_u32 s98, s66, 0x12d00000
	s_addc_u32 s99, s67, 0
	s_add_u32 s98, s98, vcc_hi
	s_addc_u32 s99, s99, 0
	s_add_u32 s98, s98, vcc_lo
	s_addc_u32 s99, s99, 0
	s_waitcnt lgkmcnt(0)
	v_cvt_pk_bf16_f32 v84, v52, v53
	v_cvt_pk_bf16_f32 v85, v54, v55
	v_cvt_pk_bf16_f32 v86, v56, v57
	v_cvt_pk_bf16_f32 v87, v58, v59
	v_cvt_pk_bf16_f32 v88, v60, v61
	v_cvt_pk_bf16_f32 v89, v62, v63
	v_cvt_pk_bf16_f32 v90, v64, v65
	v_cvt_pk_bf16_f32 v91, v66, v67
	v_cvt_pk_bf16_f32 v92, v68, v69
	v_cvt_pk_bf16_f32 v93, v70, v71
	v_cvt_pk_bf16_f32 v94, v72, v73
	v_cvt_pk_bf16_f32 v95, v74, v75
	v_cvt_pk_bf16_f32 v96, v76, v77
	v_cvt_pk_bf16_f32 v97, v78, v79
	v_cvt_pk_bf16_f32 v98, v80, v81
	v_cvt_pk_bf16_f32 v99, v82, v83
	global_store_dwordx4 v16, v[84:87], s[98:99] nt
	global_store_dwordx4 v17, v[88:91], s[98:99] nt
	global_store_dwordx4 v18, v[92:95], s[98:99] nt
	global_store_dwordx4 v19, v[96:99], s[98:99] nt
	s_waitcnt vmcnt(23)
	ds_write_b32 v14, v100 offset:0
	ds_write_b32 v14, v101 offset:4
	ds_write_b32 v14, v102 offset:8
	ds_write_b32 v14, v103 offset:12
	s_waitcnt vmcnt(22)
	ds_write_b32 v14, v104 offset:1056
	ds_write_b32 v14, v105 offset:1060
	ds_write_b32 v14, v106 offset:1064
	ds_write_b32 v14, v107 offset:1068
	s_waitcnt vmcnt(21)
	ds_write_b32 v14, v108 offset:2112
	ds_write_b32 v14, v109 offset:2116
	ds_write_b32 v14, v110 offset:2120
	ds_write_b32 v14, v111 offset:2124
	s_waitcnt vmcnt(20)
	ds_write_b32 v14, v112 offset:3168
	ds_write_b32 v14, v113 offset:3172
	ds_write_b32 v14, v114 offset:3176
	ds_write_b32 v14, v115 offset:3180
	s_waitcnt vmcnt(19)
	ds_write_b32 v14, v116 offset:4224
	ds_write_b32 v14, v117 offset:4228
	ds_write_b32 v14, v118 offset:4232
	ds_write_b32 v14, v119 offset:4236
	s_waitcnt vmcnt(18)
	ds_write_b32 v14, v120 offset:5280
	ds_write_b32 v14, v121 offset:5284
	ds_write_b32 v14, v122 offset:5288
	ds_write_b32 v14, v123 offset:5292
	s_waitcnt vmcnt(17)
	ds_write_b32 v14, v124 offset:6336
	ds_write_b32 v14, v125 offset:6340
	ds_write_b32 v14, v126 offset:6344
	ds_write_b32 v14, v127 offset:6348
	s_waitcnt vmcnt(16)
	ds_write_b32 v14, v128 offset:7392
	ds_write_b32 v14, v129 offset:7396
	ds_write_b32 v14, v130 offset:7400
	ds_write_b32 v14, v131 offset:7404
	s_add_u32 s95, s94, 0x4400
	s_lshr_b32 vcc_lo, s95, 7
	s_and_b32 vcc_hi, s95, 0x7f
	s_lshl_b32 vcc_lo, vcc_lo, 20
	s_lshl_b32 vcc_hi, vcc_hi, 7
	s_add_u32 s96, s100, vcc_lo
	s_addc_u32 s97, s101, 0
	s_add_u32 s96, s96, vcc_hi
	s_addc_u32 s97, s97, 0
	global_load_dwordx4 v[100:103], v6, s[96:97] nt
	global_load_dwordx4 v[104:107], v7, s[96:97] nt
	global_load_dwordx4 v[108:111], v8, s[96:97] nt
	global_load_dwordx4 v[112:115], v9, s[96:97] nt
	global_load_dwordx4 v[116:119], v10, s[96:97] nt
	global_load_dwordx4 v[120:123], v11, s[96:97] nt
	global_load_dwordx4 v[124:127], v12, s[96:97] nt
	global_load_dwordx4 v[128:131], v13, s[96:97] nt
	ds_read2_b32 v[52:53], v15 offset0:0 offset1:33
	ds_read2_b32 v[54:55], v15 offset0:66 offset1:99
	ds_read2_b32 v[56:57], v15 offset0:132 offset1:165
	ds_read2_b32 v[58:59], v15 offset0:198 offset1:231
	ds_read2_b32 v[60:61], v15 offset0:8 offset1:41
	ds_read2_b32 v[62:63], v15 offset0:74 offset1:107
	ds_read2_b32 v[64:65], v15 offset0:140 offset1:173
	ds_read2_b32 v[66:67], v15 offset0:206 offset1:239
	ds_read2_b32 v[68:69], v15 offset0:16 offset1:49
	ds_read2_b32 v[70:71], v15 offset0:82 offset1:115
	ds_read2_b32 v[72:73], v15 offset0:148 offset1:181
	ds_read2_b32 v[74:75], v15 offset0:214 offset1:247
	ds_read2_b32 v[76:77], v15 offset0:24 offset1:57
	ds_read2_b32 v[78:79], v15 offset0:90 offset1:123
	ds_read2_b32 v[80:81], v15 offset0:156 offset1:189
	ds_read2_b32 v[82:83], v15 offset0:222 offset1:255
	s_add_u32 s95, s94, 0x3c00
	s_lshr_b32 vcc_lo, s95, 7
	s_and_b32 vcc_hi, s95, 0x7f
	s_mul_i32 vcc_hi, vcc_hi, 0xac000
	s_lshl_b32 vcc_lo, vcc_lo, 7
	s_add_u32 s98, s66, 0x12d00000
	s_addc_u32 s99, s67, 0
	s_add_u32 s98, s98, vcc_hi
	s_addc_u32 s99, s99, 0
	s_add_u32 s98, s98, vcc_lo
	s_addc_u32 s99, s99, 0
	s_waitcnt lgkmcnt(0)
	v_cvt_pk_bf16_f32 v84, v52, v53
	v_cvt_pk_bf16_f32 v85, v54, v55
	v_cvt_pk_bf16_f32 v86, v56, v57
	v_cvt_pk_bf16_f32 v87, v58, v59
	v_cvt_pk_bf16_f32 v88, v60, v61
	v_cvt_pk_bf16_f32 v89, v62, v63
	v_cvt_pk_bf16_f32 v90, v64, v65
	v_cvt_pk_bf16_f32 v91, v66, v67
	v_cvt_pk_bf16_f32 v92, v68, v69
	v_cvt_pk_bf16_f32 v93, v70, v71
	v_cvt_pk_bf16_f32 v94, v72, v73
	v_cvt_pk_bf16_f32 v95, v74, v75
	v_cvt_pk_bf16_f32 v96, v76, v77
	v_cvt_pk_bf16_f32 v97, v78, v79
	v_cvt_pk_bf16_f32 v98, v80, v81
	v_cvt_pk_bf16_f32 v99, v82, v83
	global_store_dwordx4 v16, v[84:87], s[98:99] nt
	global_store_dwordx4 v17, v[88:91], s[98:99] nt
	global_store_dwordx4 v18, v[92:95], s[98:99] nt
	global_store_dwordx4 v19, v[96:99], s[98:99] nt
	s_waitcnt vmcnt(23)
	ds_write_b32 v14, v20 offset:0
	ds_write_b32 v14, v21 offset:4
	ds_write_b32 v14, v22 offset:8
	ds_write_b32 v14, v23 offset:12
	s_waitcnt vmcnt(22)
	ds_write_b32 v14, v24 offset:1056
	ds_write_b32 v14, v25 offset:1060
	ds_write_b32 v14, v26 offset:1064
	ds_write_b32 v14, v27 offset:1068
	s_waitcnt vmcnt(21)
	ds_write_b32 v14, v28 offset:2112
	ds_write_b32 v14, v29 offset:2116
	ds_write_b32 v14, v30 offset:2120
	ds_write_b32 v14, v31 offset:2124
	s_waitcnt vmcnt(20)
	ds_write_b32 v14, v32 offset:3168
	ds_write_b32 v14, v33 offset:3172
	ds_write_b32 v14, v34 offset:3176
	ds_write_b32 v14, v35 offset:3180
	s_waitcnt vmcnt(19)
	ds_write_b32 v14, v36 offset:4224
	ds_write_b32 v14, v37 offset:4228
	ds_write_b32 v14, v38 offset:4232
	ds_write_b32 v14, v39 offset:4236
	s_waitcnt vmcnt(18)
	ds_write_b32 v14, v40 offset:5280
	ds_write_b32 v14, v41 offset:5284
	ds_write_b32 v14, v42 offset:5288
	ds_write_b32 v14, v43 offset:5292
	s_waitcnt vmcnt(17)
	ds_write_b32 v14, v44 offset:6336
	ds_write_b32 v14, v45 offset:6340
	ds_write_b32 v14, v46 offset:6344
	ds_write_b32 v14, v47 offset:6348
	s_waitcnt vmcnt(16)
	ds_write_b32 v14, v48 offset:7392
	ds_write_b32 v14, v49 offset:7396
	ds_write_b32 v14, v50 offset:7400
	ds_write_b32 v14, v51 offset:7404
	s_add_u32 s95, s94, 0x4800
	s_lshr_b32 vcc_lo, s95, 7
	s_and_b32 vcc_hi, s95, 0x7f
	s_lshl_b32 vcc_lo, vcc_lo, 20
	s_lshl_b32 vcc_hi, vcc_hi, 7
	s_add_u32 s96, s100, vcc_lo
	s_addc_u32 s97, s101, 0
	s_add_u32 s96, s96, vcc_hi
	s_addc_u32 s97, s97, 0
	global_load_dwordx4 v[20:23], v6, s[96:97] nt
	global_load_dwordx4 v[24:27], v7, s[96:97] nt
	global_load_dwordx4 v[28:31], v8, s[96:97] nt
	global_load_dwordx4 v[32:35], v9, s[96:97] nt
	global_load_dwordx4 v[36:39], v10, s[96:97] nt
	global_load_dwordx4 v[40:43], v11, s[96:97] nt
	global_load_dwordx4 v[44:47], v12, s[96:97] nt
	global_load_dwordx4 v[48:51], v13, s[96:97] nt
	ds_read2_b32 v[52:53], v15 offset0:0 offset1:33
	ds_read2_b32 v[54:55], v15 offset0:66 offset1:99
	ds_read2_b32 v[56:57], v15 offset0:132 offset1:165
	ds_read2_b32 v[58:59], v15 offset0:198 offset1:231
	ds_read2_b32 v[60:61], v15 offset0:8 offset1:41
	ds_read2_b32 v[62:63], v15 offset0:74 offset1:107
	ds_read2_b32 v[64:65], v15 offset0:140 offset1:173
	ds_read2_b32 v[66:67], v15 offset0:206 offset1:239
	ds_read2_b32 v[68:69], v15 offset0:16 offset1:49
	ds_read2_b32 v[70:71], v15 offset0:82 offset1:115
	ds_read2_b32 v[72:73], v15 offset0:148 offset1:181
	ds_read2_b32 v[74:75], v15 offset0:214 offset1:247
	ds_read2_b32 v[76:77], v15 offset0:24 offset1:57
	ds_read2_b32 v[78:79], v15 offset0:90 offset1:123
	ds_read2_b32 v[80:81], v15 offset0:156 offset1:189
	ds_read2_b32 v[82:83], v15 offset0:222 offset1:255
	s_add_u32 s95, s94, 0x4000
	s_lshr_b32 vcc_lo, s95, 7
	s_and_b32 vcc_hi, s95, 0x7f
	s_mul_i32 vcc_hi, vcc_hi, 0xac000
	s_lshl_b32 vcc_lo, vcc_lo, 7
	s_add_u32 s98, s66, 0x12d00000
	s_addc_u32 s99, s67, 0
	s_add_u32 s98, s98, vcc_hi
	s_addc_u32 s99, s99, 0
	s_add_u32 s98, s98, vcc_lo
	s_addc_u32 s99, s99, 0
	s_waitcnt lgkmcnt(0)
	v_cvt_pk_bf16_f32 v84, v52, v53
	v_cvt_pk_bf16_f32 v85, v54, v55
	v_cvt_pk_bf16_f32 v86, v56, v57
	v_cvt_pk_bf16_f32 v87, v58, v59
	v_cvt_pk_bf16_f32 v88, v60, v61
	v_cvt_pk_bf16_f32 v89, v62, v63
	v_cvt_pk_bf16_f32 v90, v64, v65
	v_cvt_pk_bf16_f32 v91, v66, v67
	v_cvt_pk_bf16_f32 v92, v68, v69
	v_cvt_pk_bf16_f32 v93, v70, v71
	v_cvt_pk_bf16_f32 v94, v72, v73
	v_cvt_pk_bf16_f32 v95, v74, v75
	v_cvt_pk_bf16_f32 v96, v76, v77
	v_cvt_pk_bf16_f32 v97, v78, v79
	v_cvt_pk_bf16_f32 v98, v80, v81
	v_cvt_pk_bf16_f32 v99, v82, v83
	global_store_dwordx4 v16, v[84:87], s[98:99] nt
	global_store_dwordx4 v17, v[88:91], s[98:99] nt
	global_store_dwordx4 v18, v[92:95], s[98:99] nt
	global_store_dwordx4 v19, v[96:99], s[98:99] nt
	s_waitcnt vmcnt(23)
	ds_write_b32 v14, v100 offset:0
	ds_write_b32 v14, v101 offset:4
	ds_write_b32 v14, v102 offset:8
	ds_write_b32 v14, v103 offset:12
	s_waitcnt vmcnt(22)
	ds_write_b32 v14, v104 offset:1056
	ds_write_b32 v14, v105 offset:1060
	ds_write_b32 v14, v106 offset:1064
	ds_write_b32 v14, v107 offset:1068
	s_waitcnt vmcnt(21)
	ds_write_b32 v14, v108 offset:2112
	ds_write_b32 v14, v109 offset:2116
	ds_write_b32 v14, v110 offset:2120
	ds_write_b32 v14, v111 offset:2124
	s_waitcnt vmcnt(20)
	ds_write_b32 v14, v112 offset:3168
	ds_write_b32 v14, v113 offset:3172
	ds_write_b32 v14, v114 offset:3176
	ds_write_b32 v14, v115 offset:3180
	s_waitcnt vmcnt(19)
	ds_write_b32 v14, v116 offset:4224
	ds_write_b32 v14, v117 offset:4228
	ds_write_b32 v14, v118 offset:4232
	ds_write_b32 v14, v119 offset:4236
	s_waitcnt vmcnt(18)
	ds_write_b32 v14, v120 offset:5280
	ds_write_b32 v14, v121 offset:5284
	ds_write_b32 v14, v122 offset:5288
	ds_write_b32 v14, v123 offset:5292
	s_waitcnt vmcnt(17)
	ds_write_b32 v14, v124 offset:6336
	ds_write_b32 v14, v125 offset:6340
	ds_write_b32 v14, v126 offset:6344
	ds_write_b32 v14, v127 offset:6348
	s_waitcnt vmcnt(16)
	ds_write_b32 v14, v128 offset:7392
	ds_write_b32 v14, v129 offset:7396
	ds_write_b32 v14, v130 offset:7400
	ds_write_b32 v14, v131 offset:7404
	s_add_u32 s95, s94, 0x4c00
	s_lshr_b32 vcc_lo, s95, 7
	s_and_b32 vcc_hi, s95, 0x7f
	s_lshl_b32 vcc_lo, vcc_lo, 20
	s_lshl_b32 vcc_hi, vcc_hi, 7
	s_add_u32 s96, s100, vcc_lo
	s_addc_u32 s97, s101, 0
	s_add_u32 s96, s96, vcc_hi
	s_addc_u32 s97, s97, 0
	global_load_dwordx4 v[100:103], v6, s[96:97] nt
	global_load_dwordx4 v[104:107], v7, s[96:97] nt
	global_load_dwordx4 v[108:111], v8, s[96:97] nt
	global_load_dwordx4 v[112:115], v9, s[96:97] nt
	global_load_dwordx4 v[116:119], v10, s[96:97] nt
	global_load_dwordx4 v[120:123], v11, s[96:97] nt
	global_load_dwordx4 v[124:127], v12, s[96:97] nt
	global_load_dwordx4 v[128:131], v13, s[96:97] nt
	ds_read2_b32 v[52:53], v15 offset0:0 offset1:33
	ds_read2_b32 v[54:55], v15 offset0:66 offset1:99
	ds_read2_b32 v[56:57], v15 offset0:132 offset1:165
	ds_read2_b32 v[58:59], v15 offset0:198 offset1:231
	ds_read2_b32 v[60:61], v15 offset0:8 offset1:41
	ds_read2_b32 v[62:63], v15 offset0:74 offset1:107
	ds_read2_b32 v[64:65], v15 offset0:140 offset1:173
	ds_read2_b32 v[66:67], v15 offset0:206 offset1:239
	ds_read2_b32 v[68:69], v15 offset0:16 offset1:49
	ds_read2_b32 v[70:71], v15 offset0:82 offset1:115
	ds_read2_b32 v[72:73], v15 offset0:148 offset1:181
	ds_read2_b32 v[74:75], v15 offset0:214 offset1:247
	ds_read2_b32 v[76:77], v15 offset0:24 offset1:57
	ds_read2_b32 v[78:79], v15 offset0:90 offset1:123
	ds_read2_b32 v[80:81], v15 offset0:156 offset1:189
	ds_read2_b32 v[82:83], v15 offset0:222 offset1:255
	s_add_u32 s95, s94, 0x4400
	s_lshr_b32 vcc_lo, s95, 7
	s_and_b32 vcc_hi, s95, 0x7f
	s_mul_i32 vcc_hi, vcc_hi, 0xac000
	s_lshl_b32 vcc_lo, vcc_lo, 7
	s_add_u32 s98, s66, 0x12d00000
	s_addc_u32 s99, s67, 0
	s_add_u32 s98, s98, vcc_hi
	s_addc_u32 s99, s99, 0
	s_add_u32 s98, s98, vcc_lo
	s_addc_u32 s99, s99, 0
	s_waitcnt lgkmcnt(0)
	v_cvt_pk_bf16_f32 v84, v52, v53
	v_cvt_pk_bf16_f32 v85, v54, v55
	v_cvt_pk_bf16_f32 v86, v56, v57
	v_cvt_pk_bf16_f32 v87, v58, v59
	v_cvt_pk_bf16_f32 v88, v60, v61
	v_cvt_pk_bf16_f32 v89, v62, v63
	v_cvt_pk_bf16_f32 v90, v64, v65
	v_cvt_pk_bf16_f32 v91, v66, v67
	v_cvt_pk_bf16_f32 v92, v68, v69
	v_cvt_pk_bf16_f32 v93, v70, v71
	v_cvt_pk_bf16_f32 v94, v72, v73
	v_cvt_pk_bf16_f32 v95, v74, v75
	v_cvt_pk_bf16_f32 v96, v76, v77
	v_cvt_pk_bf16_f32 v97, v78, v79
	v_cvt_pk_bf16_f32 v98, v80, v81
	v_cvt_pk_bf16_f32 v99, v82, v83
	global_store_dwordx4 v16, v[84:87], s[98:99] nt
	global_store_dwordx4 v17, v[88:91], s[98:99] nt
	global_store_dwordx4 v18, v[92:95], s[98:99] nt
	global_store_dwordx4 v19, v[96:99], s[98:99] nt
	s_waitcnt vmcnt(23)
	ds_write_b32 v14, v20 offset:0
	ds_write_b32 v14, v21 offset:4
	ds_write_b32 v14, v22 offset:8
	ds_write_b32 v14, v23 offset:12
	s_waitcnt vmcnt(22)
	ds_write_b32 v14, v24 offset:1056
	ds_write_b32 v14, v25 offset:1060
	ds_write_b32 v14, v26 offset:1064
	ds_write_b32 v14, v27 offset:1068
	s_waitcnt vmcnt(21)
	ds_write_b32 v14, v28 offset:2112
	ds_write_b32 v14, v29 offset:2116
	ds_write_b32 v14, v30 offset:2120
	ds_write_b32 v14, v31 offset:2124
	s_waitcnt vmcnt(20)
	ds_write_b32 v14, v32 offset:3168
	ds_write_b32 v14, v33 offset:3172
	ds_write_b32 v14, v34 offset:3176
	ds_write_b32 v14, v35 offset:3180
	s_waitcnt vmcnt(19)
	ds_write_b32 v14, v36 offset:4224
	ds_write_b32 v14, v37 offset:4228
	ds_write_b32 v14, v38 offset:4232
	ds_write_b32 v14, v39 offset:4236
	s_waitcnt vmcnt(18)
	ds_write_b32 v14, v40 offset:5280
	ds_write_b32 v14, v41 offset:5284
	ds_write_b32 v14, v42 offset:5288
	ds_write_b32 v14, v43 offset:5292
	s_waitcnt vmcnt(17)
	ds_write_b32 v14, v44 offset:6336
	ds_write_b32 v14, v45 offset:6340
	ds_write_b32 v14, v46 offset:6344
	ds_write_b32 v14, v47 offset:6348
	s_waitcnt vmcnt(16)
	ds_write_b32 v14, v48 offset:7392
	ds_write_b32 v14, v49 offset:7396
	ds_write_b32 v14, v50 offset:7400
	ds_write_b32 v14, v51 offset:7404
	ds_read2_b32 v[52:53], v15 offset0:0 offset1:33
	ds_read2_b32 v[54:55], v15 offset0:66 offset1:99
	ds_read2_b32 v[56:57], v15 offset0:132 offset1:165
	ds_read2_b32 v[58:59], v15 offset0:198 offset1:231
	ds_read2_b32 v[60:61], v15 offset0:8 offset1:41
	ds_read2_b32 v[62:63], v15 offset0:74 offset1:107
	ds_read2_b32 v[64:65], v15 offset0:140 offset1:173
	ds_read2_b32 v[66:67], v15 offset0:206 offset1:239
	ds_read2_b32 v[68:69], v15 offset0:16 offset1:49
	ds_read2_b32 v[70:71], v15 offset0:82 offset1:115
	ds_read2_b32 v[72:73], v15 offset0:148 offset1:181
	ds_read2_b32 v[74:75], v15 offset0:214 offset1:247
	ds_read2_b32 v[76:77], v15 offset0:24 offset1:57
	ds_read2_b32 v[78:79], v15 offset0:90 offset1:123
	ds_read2_b32 v[80:81], v15 offset0:156 offset1:189
	ds_read2_b32 v[82:83], v15 offset0:222 offset1:255
	s_add_u32 s95, s94, 0x4800
	s_lshr_b32 vcc_lo, s95, 7
	s_and_b32 vcc_hi, s95, 0x7f
	s_mul_i32 vcc_hi, vcc_hi, 0xac000
	s_lshl_b32 vcc_lo, vcc_lo, 7
	s_add_u32 s98, s66, 0x12d00000
	s_addc_u32 s99, s67, 0
	s_add_u32 s98, s98, vcc_hi
	s_addc_u32 s99, s99, 0
	s_add_u32 s98, s98, vcc_lo
	s_addc_u32 s99, s99, 0
	s_waitcnt lgkmcnt(0)
	v_cvt_pk_bf16_f32 v84, v52, v53
	v_cvt_pk_bf16_f32 v85, v54, v55
	v_cvt_pk_bf16_f32 v86, v56, v57
	v_cvt_pk_bf16_f32 v87, v58, v59
	v_cvt_pk_bf16_f32 v88, v60, v61
	v_cvt_pk_bf16_f32 v89, v62, v63
	v_cvt_pk_bf16_f32 v90, v64, v65
	v_cvt_pk_bf16_f32 v91, v66, v67
	v_cvt_pk_bf16_f32 v92, v68, v69
	v_cvt_pk_bf16_f32 v93, v70, v71
	v_cvt_pk_bf16_f32 v94, v72, v73
	v_cvt_pk_bf16_f32 v95, v74, v75
	v_cvt_pk_bf16_f32 v96, v76, v77
	v_cvt_pk_bf16_f32 v97, v78, v79
	v_cvt_pk_bf16_f32 v98, v80, v81
	v_cvt_pk_bf16_f32 v99, v82, v83
	global_store_dwordx4 v16, v[84:87], s[98:99] nt
	global_store_dwordx4 v17, v[88:91], s[98:99] nt
	global_store_dwordx4 v18, v[92:95], s[98:99] nt
	global_store_dwordx4 v19, v[96:99], s[98:99] nt
	s_waitcnt vmcnt(15)
	ds_write_b32 v14, v100 offset:0
	ds_write_b32 v14, v101 offset:4
	ds_write_b32 v14, v102 offset:8
	ds_write_b32 v14, v103 offset:12
	s_waitcnt vmcnt(14)
	ds_write_b32 v14, v104 offset:1056
	ds_write_b32 v14, v105 offset:1060
	ds_write_b32 v14, v106 offset:1064
	ds_write_b32 v14, v107 offset:1068
	s_waitcnt vmcnt(13)
	ds_write_b32 v14, v108 offset:2112
	ds_write_b32 v14, v109 offset:2116
	ds_write_b32 v14, v110 offset:2120
	ds_write_b32 v14, v111 offset:2124
	s_waitcnt vmcnt(12)
	ds_write_b32 v14, v112 offset:3168
	ds_write_b32 v14, v113 offset:3172
	ds_write_b32 v14, v114 offset:3176
	ds_write_b32 v14, v115 offset:3180
	s_waitcnt vmcnt(11)
	ds_write_b32 v14, v116 offset:4224
	ds_write_b32 v14, v117 offset:4228
	ds_write_b32 v14, v118 offset:4232
	ds_write_b32 v14, v119 offset:4236
	s_waitcnt vmcnt(10)
	ds_write_b32 v14, v120 offset:5280
	ds_write_b32 v14, v121 offset:5284
	ds_write_b32 v14, v122 offset:5288
	ds_write_b32 v14, v123 offset:5292
	s_waitcnt vmcnt(9)
	ds_write_b32 v14, v124 offset:6336
	ds_write_b32 v14, v125 offset:6340
	ds_write_b32 v14, v126 offset:6344
	ds_write_b32 v14, v127 offset:6348
	s_waitcnt vmcnt(8)
	ds_write_b32 v14, v128 offset:7392
	ds_write_b32 v14, v129 offset:7396
	ds_write_b32 v14, v130 offset:7400
	ds_write_b32 v14, v131 offset:7404
	ds_read2_b32 v[52:53], v15 offset0:0 offset1:33
	ds_read2_b32 v[54:55], v15 offset0:66 offset1:99
	ds_read2_b32 v[56:57], v15 offset0:132 offset1:165
	ds_read2_b32 v[58:59], v15 offset0:198 offset1:231
	ds_read2_b32 v[60:61], v15 offset0:8 offset1:41
	ds_read2_b32 v[62:63], v15 offset0:74 offset1:107
	ds_read2_b32 v[64:65], v15 offset0:140 offset1:173
	ds_read2_b32 v[66:67], v15 offset0:206 offset1:239
	ds_read2_b32 v[68:69], v15 offset0:16 offset1:49
	ds_read2_b32 v[70:71], v15 offset0:82 offset1:115
	ds_read2_b32 v[72:73], v15 offset0:148 offset1:181
	ds_read2_b32 v[74:75], v15 offset0:214 offset1:247
	ds_read2_b32 v[76:77], v15 offset0:24 offset1:57
	ds_read2_b32 v[78:79], v15 offset0:90 offset1:123
	ds_read2_b32 v[80:81], v15 offset0:156 offset1:189
	ds_read2_b32 v[82:83], v15 offset0:222 offset1:255
	s_add_u32 s95, s94, 0x4c00
	s_lshr_b32 vcc_lo, s95, 7
	s_and_b32 vcc_hi, s95, 0x7f
	s_mul_i32 vcc_hi, vcc_hi, 0xac000
	s_lshl_b32 vcc_lo, vcc_lo, 7
	s_add_u32 s98, s66, 0x12d00000
	s_addc_u32 s99, s67, 0
	s_add_u32 s98, s98, vcc_hi
	s_addc_u32 s99, s99, 0
	s_add_u32 s98, s98, vcc_lo
	s_addc_u32 s99, s99, 0
	s_waitcnt lgkmcnt(0)
	v_cvt_pk_bf16_f32 v84, v52, v53
	v_cvt_pk_bf16_f32 v85, v54, v55
	v_cvt_pk_bf16_f32 v86, v56, v57
	v_cvt_pk_bf16_f32 v87, v58, v59
	v_cvt_pk_bf16_f32 v88, v60, v61
	v_cvt_pk_bf16_f32 v89, v62, v63
	v_cvt_pk_bf16_f32 v90, v64, v65
	v_cvt_pk_bf16_f32 v91, v66, v67
	v_cvt_pk_bf16_f32 v92, v68, v69
	v_cvt_pk_bf16_f32 v93, v70, v71
	v_cvt_pk_bf16_f32 v94, v72, v73
	v_cvt_pk_bf16_f32 v95, v74, v75
	v_cvt_pk_bf16_f32 v96, v76, v77
	v_cvt_pk_bf16_f32 v97, v78, v79
	v_cvt_pk_bf16_f32 v98, v80, v81
	v_cvt_pk_bf16_f32 v99, v82, v83
	global_store_dwordx4 v16, v[84:87], s[98:99] nt
	global_store_dwordx4 v17, v[88:91], s[98:99] nt
	global_store_dwordx4 v18, v[92:95], s[98:99] nt
	global_store_dwordx4 v19, v[96:99], s[98:99] nt
